# barrier polling pipelined: 4 polls in flight as LDS-DMA dword loads into spare LDS words (no VGPR destination, no drain at exit), checked via ds_read; plus dead v_mov removal in conv-gate epilogue
# baseline (speedup 1.0000x reference)
; #define REP(bit) for (int rep_ = 0; rep_ < (((DUP) & (bit)) ? 2 : 1); ++rep_)
; __device__ __forceinline__ void xcd_barrier(const XcdBarrier& b) {
;     asm volatile("s_waitcnt vmcnt(0)" ::: "memory");
;     __syncthreads();
;     if (threadIdx.x == 0) {
;         unsigned* bar = b.bar;
;         __builtin_amdgcn_s_waitcnt(0);
;         unsigned nloc = b.st[0], nx = b.st[1];
;         if (nloc == 0u) { xcd_barrier_complete(bar, b.x, nloc, nx); b.st[0] = nloc; b.st[1] = nx; }
;         const unsigned old = xb_add(&bar[XB_XSUB(b.x)], 1u);
;         const unsigned gen = old / nloc;
;         if (old + 1u == (gen + 1u) * nloc) {
;             __builtin_amdgcn_fence(__ATOMIC_RELEASE, "agent");
;             asm volatile("s_waitcnt vmcnt(0)" ::: "memory");
;             const unsigned og = xb_add(&bar[XB_TOP], 1u);
;             const unsigned tg = og / nx;
;             if (og + 1u == (tg + 1u) * nx) xb_add(&bar[XB_TOPGEN], 1u);
;             else XB_SPIN(xb_ld(&bar[XB_TOPGEN]) == tg, bar);
;             __builtin_amdgcn_fence(__ATOMIC_ACQUIRE, "agent");
;             xb_add(&bar[XB_XGEN(b.x)], 1u);
;             asm volatile("s_waitcnt vmcnt(0)" ::: "memory");
;         } else {
;             XB_SPIN(xb_ld(&bar[XB_XGEN(b.x)]) == gen, bar);
;             __builtin_amdgcn_fence(__ATOMIC_ACQUIRE, "agent");
;             asm volatile("s_waitcnt vmcnt(0)" ::: "memory");
;         }
;     }
;     __syncthreads();
; }
; __global__ void __launch_bounds__(NTHR, 2) fwd_megakernel(Args args) {
;     ...
;         if (even) {
;             if constexpr ((DUP) & 4) { Ctx cd = mkctx(lds); cd.wr = (args.ws == nullptr); prep_even(cd, args); }
;             if constexpr (PH & 4) prep_even(mkctx(lds), args);
;             GSYNC();
;             if constexpr (PH & 8) REP(8) sb_attention(mkctx(lds), (const bf16*)R, (const bf16*)(R + 32 * MiB), (const bf16*)(R + 64 * MiB), OUTB);
;             if constexpr ((DUP) & 32) la2<128, false, true>(mkctx(lds), (bf16*)(R + 256 * MiB), nullptr);
;             if constexpr (PH & 32) la2<128, false>(mkctx(lds), (bf16*)(R + 256 * MiB), nullptr);
;             GSYNC();
;             if constexpr (PH & 64) REP(64) la3<128>(mkctx(lds), (const bf16*)(R + 96 * MiB), (const bf16*)(R + 128 * MiB), (const bf16*)(R + 160 * MiB), (const bf16*)(R + 256 * MiB), args.in[5], (const bf16*)(R + 192 * MiB), 512, OUTB, 512);
;             GSYNC();
;         } else {
.Lnb_loop_1:
	s_sub_u32 s5, s2, 36
	v_mov_b32_e32 v9, 0x2404
	v_mov_b32_e32 v10, s5
	s_mov_b32 m0, s5
	s_nop 0
	global_load_lds_dword v9, s[12:13] sc1
	s_add_u32 m0, s5, 4
	s_nop 0
	global_load_lds_dword v9, s[12:13] sc1
	s_add_u32 m0, s5, 8
	s_nop 0
	global_load_lds_dword v9, s[12:13] sc1
.Lnb_ring_1:
	s_add_u32 m0, s5, 12
	s_nop 0
	global_load_lds_dword v9, s[12:13] sc1
	s_waitcnt vmcnt(3)
	ds_read_b32 v8, v10
	s_waitcnt lgkmcnt(0)
	v_cmp_lt_u32_e32 vcc, v8, v7
	s_cbranch_vccz .Lnb_done_1
	s_mov_b32 m0, s5
	s_nop 0
	global_load_lds_dword v9, s[12:13] sc1
	s_waitcnt vmcnt(3)
	ds_read_b32 v8, v10 offset:4
	s_waitcnt lgkmcnt(0)
	v_cmp_lt_u32_e32 vcc, v8, v7
	s_cbranch_vccz .Lnb_done_1
	s_add_u32 m0, s5, 4
	s_nop 0
	global_load_lds_dword v9, s[12:13] sc1
	s_waitcnt vmcnt(3)
	ds_read_b32 v8, v10 offset:8
	s_waitcnt lgkmcnt(0)
	v_cmp_lt_u32_e32 vcc, v8, v7
	s_cbranch_vccz .Lnb_done_1
	s_add_u32 m0, s5, 8
	s_nop 0
	global_load_lds_dword v9, s[12:13] sc1
	s_waitcnt vmcnt(3)
	ds_read_b32 v8, v10 offset:12
	s_waitcnt lgkmcnt(0)
	v_cmp_lt_u32_e32 vcc, v8, v7
	s_cbranch_vccz .Lnb_done_1
	s_add_u32 s8, s8, 1
	s_cmp_gt_u32 s8, 0x40000
	s_cbranch_scc1 .Lnb_done_1
	s_branch .Lnb_ring_1
.Lnb_done_1:
.LBB0_214:
	s_or_b64 exec, exec, s[0:1]
	v_readlane_b32 s0, v254, 61
	v_readlane_b32 s1, v254, 62
	s_xor_b64 s[0:1], s[0:1], -1
	s_and_b64 vcc, exec, s[0:1]
	v_readlane_b32 s0, v253, 42
	v_readlane_b32 s1, v253, 43
	s_mov_b64 s[6:7], -1
	s_waitcnt lgkmcnt(0)
	v_cndmask_b32_e64 v0, 0, 1, s[0:1]
	v_cmp_ne_u32_e64 s[24:25], 1, v0
	s_barrier
	s_cbranch_vccz .LBB0_393
	v_mov_b32_e32 v52, v186
	s_load_dword s66, s[70:71], 0x0
	v_writelane_b32 v254, s24, 63
	s_mov_b64 s[20:21], 0x1000
	s_and_b64 vcc, exec, s[24:25]
	v_writelane_b32 v255, s25, 0
	v_readfirstlane_b32 s0, v52
	s_mov_b64 s[22:23], 0x3c00
	s_mov_b64 s[24:25], 0x10000
	s_mov_b64 s[30:31], 0x1400
	s_mov_b64 s[34:35], 0x2000
	s_mov_b64 s[36:37], 0x2400
	s_mov_b64 s[54:55], 0x2800
	s_mov_b64 s[50:51], 0x2c00
	s_mov_b64 s[48:49], 0x1800
	s_mov_b64 s[56:57], 0x1c00
	s_mov_b64 s[58:59], 0x3800
	s_mov_b64 s[62:63], 0x3000
	s_cbranch_vccnz .LBB0_218
; DI void vl_load(unsigned char* VL, const bf16* src, int tid) {
;     u32x4 t[8];
; #pragma unroll
;     for (int i = 0; i < 8; ++i) t[i] = *(const u32x4*)(src + (size_t)(tid + 512 * i) * 8);
; #pragma unroll
;     for (int i = 0; i < 8; ++i) { const int q = tid + 512 * i, row = q >> 3, ch = q & 7; *(u32x4*)(VL + row * 128 + ((ch ^ (row & 7)) << 4)) = t[i]; }
; }
; DI void prep_odd(const Ctx& c, const Args& a) {
;     unsigned char* R = a.ws + WS_R;
;     bf16* gq = (bf16*)R; bf16* gk = (bf16*)(R + 32 * MiB); bf16* gv = (bf16*)(R + 64 * MiB);
;     const float* GA = (const float*)(R + 192 * MiB); float* DEC = (float*)(R + 194 * MiB); bf16* kht = (bf16*)(R + 196 * MiB);
;     float* gal = (float*)c.lds;
;     const int ch = c.tid, h = ch >> 7, d = ch & 127;
;     float wa[16];
; #pragma unroll
;     for (int r = 0; r < 16; ++r) wa[r] = a.in[8][r * 512 + ch];
;     const float ba = a.in[9][ch];
;     for (int cp = c.bid; cp < 512; cp += c.G) {
;         __syncthreads();
;         {
;             const int l31 = c.lane & 31, hi = c.lane >> 5;
;             const bf16* xn = (const bf16*)(a.ws + WS_XN) + (size_t)cp * 64 * 1024 + 128 * c.wave;
;             const bf16* w16 = (const bf16*)(a.ws + WS_WINO) + (size_t)3072 * 1024 + 128 * c.wave;
;             bf16x8 wf[8], xf[2][8];
; #pragma unroll
;             for (int kk = 0; kk < 8; ++kk) { wf[kk] = *(const bf16x8*)(w16 + (size_t)(l31 & 15) * 1024 + 16 * kk + 8 * hi);
;                 xf[0][kk] = *(const bf16x8*)(xn + (size_t)l31 * 1024 + 16 * kk + 8 * hi); xf[1][kk] = *(const bf16x8*)(xn + (size_t)(32 + l31) * 1024 + 16 * kk + 8 * hi); }
;             float* part = (float*)(c.lds + 4096) + c.wave * 1024;
	v_ashrrev_i32_e32 v53, 31, v52
	v_readlane_b32 s4, v253, 20
	v_lshlrev_b64 v[0:1], 2, v[52:53]
	v_readlane_b32 s6, v253, 22
	v_readlane_b32 s7, v253, 23
	v_readlane_b32 s5, v253, 21
	s_movk_i32 s1, 0x4000
	v_lshl_add_u64 v[2:3], s[6:7], 0, v[0:1]
	v_readlane_b32 s6, v253, 40
	v_readlane_b32 s7, v253, 41
	global_load_dword v102, v[2:3], off
	v_readlane_b32 s2, v253, 44
	v_lshl_add_u64 v[54:55], s[6:7], 0, v[0:1]
	v_lshl_add_u64 v[0:1], s[4:5], 0, v[0:1]
	v_add_co_u32_e32 v2, vcc, 0x7000, v0
	s_ashr_i32 s6, s0, 6
	s_nop 0
	v_addc_co_u32_e32 v3, vcc, 0, v1, vcc
	v_add_co_u32_e32 v4, vcc, 0x6000, v0
	s_movk_i32 s0, 0x50
	s_nop 0
	v_addc_co_u32_e32 v5, vcc, 0, v1, vcc
	v_add_co_u32_e32 v6, vcc, 0x5000, v0
	v_bfe_u32 v25, v52, 5, 1
	s_nop 0
	v_addc_co_u32_e32 v7, vcc, 0, v1, vcc
	v_add_co_u32_e32 v8, vcc, s1, v0
	v_and_b32_e32 v23, 31, v52
	s_nop 0
	v_addc_co_u32_e32 v9, vcc, 0, v1, vcc
	v_add_co_u32_e32 v10, vcc, 0x3000, v0
	v_lshrrev_b32_e32 v24, 5, v52
	s_nop 0
	v_addc_co_u32_e32 v11, vcc, 0, v1, vcc
	v_add_co_u32_e32 v12, vcc, s52, v0
	v_and_b32_e32 v32, 7, v52
	s_nop 0
	v_addc_co_u32_e32 v13, vcc, 0, v1, vcc
	v_add_co_u32_e32 v14, vcc, 0x1000, v0
	v_lshl_add_u32 v104, v52, 2, 0
	s_nop 0
	v_addc_co_u32_e32 v15, vcc, 0, v1, vcc
	global_load_dword v56, v[8:9], off offset:2048
	global_load_dword v59, v[10:11], off offset:2048
	global_load_dword v61, v[12:13], off offset:2048
	global_load_dword v58, v[14:15], off offset:2048
	global_load_dword v62, v[14:15], off
	global_load_dword v65, v[12:13], off
	global_load_dword v63, v[10:11], off
	global_load_dword v66, v[8:9], off
	global_load_dword v69, v[2:3], off offset:2048
	global_load_dword v57, v[4:5], off offset:2048
	global_load_dword v68, v[6:7], off offset:2048
	global_load_dword v70, v[6:7], off
	global_load_dword v67, v[4:5], off
	global_load_dword v71, v[2:3], off
	global_load_dword v60, v[0:1], off offset:2048
	global_load_dword v64, v[0:1], off
	v_lshlrev_b32_e32 v0, 4, v52
	v_bitop3_b32 v20, v0, s0, v194 bitop3:0x6c
	s_movk_i32 s0, 0x60
	v_bitop3_b32 v21, v0, s0, v194 bitop3:0x6c
	s_movk_i32 s0, 0x70
	v_bitop3_b32 v22, v0, s0, v0 bitop3:0xc
	s_lshl_b32 s0, s6, 7
	s_ashr_i32 s1, s0, 31
	s_lshl_b64 s[0:1], s[0:1], 1
	s_add_u32 s4, s82, s0
	s_addc_u32 s5, s83, s1
	v_and_b32_e32 v3, 0x70, v0
	v_bitop3_b32 v16, v0, 16, v194 bitop3:0x6c
	v_bitop3_b32 v17, v0, 32, v194 bitop3:0x6c
	v_bitop3_b32 v18, v0, 48, v194 bitop3:0x6c
	v_bitop3_b32 v19, v0, 64, v194 bitop3:0x6c
	s_add_u32 s0, s2, s0
	v_readlane_b32 s2, v253, 45
	v_lshlrev_b32_e32 v0, 11, v52
	s_addc_u32 s1, s2, s1
	v_and_b32_e32 v160, 0x7800, v0
	v_lshl_add_u64 v[0:1], s[0:1], 0, v[160:161]
	v_lshlrev_b32_e32 v160, 4, v25
	v_lshl_add_u64 v[72:73], v[0:1], 0, v[160:161]
	v_lshlrev_b32_e32 v0, 11, v23
	v_mov_b32_e32 v1, v161
	s_lshl_b32 s0, s6, 12
	v_lshl_add_u64 v[74:75], s[4:5], 0, v[0:1]
	s_add_i32 s0, s0, 0
	v_lshlrev_b32_e32 v0, 6, v23
	v_add3_u32 v103, s0, v0, v160
	v_add_u32_e32 v0, 0x200, v52
	v_ashrrev_i32_e32 v1, 31, v0
	v_add_u32_e32 v8, 0x800, v52
	v_lshlrev_b64 v[78:79], 4, v[0:1]
	v_ashrrev_i32_e32 v9, 31, v8
	v_ashrrev_i32_e32 v0, 3, v0
	v_lshlrev_b64 v[84:85], 4, v[8:9]
	v_add_u32_e32 v10, 0xa00, v52
	v_lshl_add_u32 v9, v0, 7, 0
	v_xor_b32_e32 v0, v0, v52
	v_add_u32_e32 v4, 0x400, v52
	v_ashrrev_i32_e32 v11, 31, v10
	v_lshlrev_b32_e32 v0, 4, v0
	v_ashrrev_i32_e32 v5, 31, v4
	v_lshlrev_b64 v[86:87], 4, v[10:11]
	v_and_b32_e32 v11, 0x70, v0
	v_ashrrev_i32_e32 v0, 3, v4
	v_lshlrev_b64 v[80:81], 4, v[4:5]
	v_add_u32_e32 v12, 0xc00, v52
	v_lshl_add_u32 v4, v0, 7, 0
	v_xor_b32_e32 v0, v0, v52
	v_add_u32_e32 v6, 0x600, v52
	v_ashrrev_i32_e32 v13, 31, v12
	v_lshlrev_b32_e32 v0, 4, v0
	v_ashrrev_i32_e32 v7, 31, v6
	v_lshlrev_b64 v[88:89], 4, v[12:13]
	v_and_b32_e32 v13, 0x70, v0
	v_ashrrev_i32_e32 v0, 3, v6
	v_lshlrev_b64 v[82:83], 4, v[6:7]
	v_add_u32_e32 v14, 0xe00, v52
	v_lshl_add_u32 v6, v0, 7, 0
	v_xor_b32_e32 v0, v0, v52
	v_ashrrev_i32_e32 v15, 31, v14
	v_lshlrev_b32_e32 v0, 4, v0
	v_lshlrev_b64 v[90:91], 4, v[14:15]
	v_and_b32_e32 v15, 0x70, v0
	v_ashrrev_i32_e32 v0, 3, v8
	v_lshl_add_u32 v8, v0, 7, 0
	v_xor_b32_e32 v0, v0, v52
	v_lshlrev_b32_e32 v0, 4, v0
	v_and_b32_e32 v27, 0x70, v0
	v_ashrrev_i32_e32 v0, 3, v10
	v_lshl_add_u32 v10, v0, 7, 0
	v_xor_b32_e32 v0, v0, v52
	v_lshlrev_b32_e32 v0, 4, v0
	v_and_b32_e32 v28, 0x70, v0
	v_ashrrev_i32_e32 v0, 3, v12
	v_lshl_add_u32 v12, v0, 7, 0
	v_xor_b32_e32 v0, v0, v52
	v_lshlrev_b32_e32 v0, 4, v0
	v_and_b32_e32 v29, 0x70, v0
	v_ashrrev_i32_e32 v0, 3, v14
	v_ashrrev_i32_e32 v1, 3, v52
	v_lshl_add_u32 v14, v0, 7, 0
	v_xor_b32_e32 v0, v0, v52
	v_lshl_add_u32 v5, v1, 7, 0
	v_xor_b32_e32 v1, v1, v52
	v_lshlrev_b32_e32 v0, 4, v0
	s_lshl_b32 s1, s6, 5
	v_lshlrev_b32_e32 v1, 4, v1
	v_and_b32_e32 v30, 0x70, v0
	v_lshl_or_b32 v0, v25, 2, s1
	v_and_b32_e32 v7, 0x70, v1
	v_ashrrev_i32_e32 v1, 31, v0
	v_readlane_b32 s4, v253, 58
	v_lshlrev_b64 v[0:1], 8, v[0:1]
	v_readlane_b32 s5, v253, 59
	v_lshlrev_b32_e32 v160, 1, v23
	s_add_i32 s0, 0, 0x10000
	v_lshl_add_u64 v[0:1], s[4:5], 0, v[0:1]
	v_lshl_add_u64 v[92:93], v[0:1], 0, v[160:161]
	v_bitop3_b32 v0, v24, v32, 1 bitop3:0x6c
	v_lshlrev_b32_e32 v106, 4, v0
	v_bitop3_b32 v0, v25, v32, 2 bitop3:0x36
	v_lshlrev_b32_e32 v107, 4, v0
	v_bitop3_b32 v0, v25, v32, 4 bitop3:0x36
	v_lshlrev_b32_e32 v2, 3, v25
	v_lshl_add_u32 v26, v52, 7, s0
	v_or_b32_e32 v31, s1, v23
	v_lshlrev_b32_e32 v108, 4, v0
	v_bitop3_b32 v0, v25, v32, 6 bitop3:0x36
	v_lshlrev_b64 v[76:77], 4, v[52:53]
	v_lshl_add_u32 v105, v31, 7, 0
	v_lshlrev_b32_e32 v109, 4, v0
	v_lshl_add_u32 v110, v23, 7, s0
	v_lshlrev_b32_e32 v160, 1, v2
	v_add_u32_e32 v111, v26, v3
	v_add_u32_e32 v112, v26, v16
	v_add_u32_e32 v113, v26, v17
	v_add_u32_e32 v114, v26, v18
	v_add_u32_e32 v115, v26, v19
	v_add_u32_e32 v116, v26, v20
	v_add_u32_e32 v117, v26, v21
	v_add_u32_e32 v118, v26, v22
	v_add_u32_e32 v119, v5, v7
	v_add_u32_e32 v120, v9, v11
	v_add_u32_e32 v121, v4, v13
	v_add_u32_e32 v122, v6, v15
	v_add_u32_e32 v123, v8, v27
	v_add_u32_e32 v124, v10, v28
	v_add_u32_e32 v125, v12, v29
	v_add_u32_e32 v126, v14, v30
	s_mov_b32 s0, s90
	v_readlane_b32 s8, v253, 24
	v_readlane_b32 s9, v253, 25
	v_readlane_b32 s10, v253, 26
	v_readlane_b32 s11, v253, 27
	v_readlane_b32 s12, v253, 28
	v_readlane_b32 s13, v253, 29
	v_readlane_b32 s14, v253, 30
	v_readlane_b32 s15, v253, 31
	v_readlane_b32 s16, v253, 32
	v_readlane_b32 s17, v253, 33
	v_readlane_b32 s18, v253, 34
	v_readlane_b32 s19, v253, 35

; DI float ex2(float x) { return __builtin_amdgcn_exp2f(x); }
; template <int DV, bool GLA, bool DRY = false> DI void la2(const Ctx& c, bf16* ST, const float* DEC) {
;     ...
;     for (int task = c.bid * NTHR + c.tid; task < ntask; task += c.G * NTHR) {
;         const int dp = task & 63, e = (task >> 6) % DV, bh = task / (64 * DV), b = bh >> 2, h = bh & 3;
;         float s0 = 0.f, s1 = 0.f;
;         f32x2 dc; { const float g = ex2(64.f * lgam2_of(h)); dc = (f32x2){g, g}; }
;         unsigned* base = (unsigned*)(ST + ((size_t)(b * 256) * 4 + h) * DV * 128 + (size_t)e * 128 + 2 * dp);
.Lnb_done_2:
.LBB0_270:
	s_or_b64 exec, exec, s[0:1]
	s_waitcnt lgkmcnt(0)
	v_mov_b32_e32 v0, v186
	v_readlane_b32 s0, v254, 60
	s_barrier
	s_nop 0
	v_add_u32_e32 v134, s0, v0
	s_mov_b32 s0, 0x20000
	v_cmp_gt_i32_e32 vcc, s0, v134
	s_and_saveexec_b64 s[0:1], vcc
	s_cbranch_execz .LBB0_275
	v_readlane_b32 s2, v254, 33
	s_lshl_b32 s4, s66, 9
	s_lshl_b32 s5, s66, 10
	v_lshl_add_u32 v135, v0, 1, s2
	s_mov_b64 s[6:7], 0

; template <int DV> DI void la3_issue(La3Stage<DV>& r, const bf16* __restrict__ QT, const bf16* __restrict__ KT, const bf16* __restrict__ VT, const bf16* __restrict__ ST, int u, int tid) {
;     const int cp = u >> 2, h = u & 3; const size_t row0 = (size_t)cp * 64;
; #pragma unroll
;     for (int i = 0; i < 2; ++i) { const int q = tid + 512 * i, row = q >> 4, ch = q & 15;
;         r.q[i] = *(const u32x4*)(QT + (row0 + row) * 512 + h * 128 + ch * 8); r.k[i] = *(const u32x4*)(KT + (row0 + row) * 512 + h * 128 + ch * 8); }
; template <int DV> DI void la3(const Ctx& c, const bf16* __restrict__ QT, const bf16* __restrict__ KT, const bf16* __restrict__ VT, const bf16* __restrict__ ST, const float* __restrict__ gain, const bf16* __restrict__ gate, int gate_ld, bf16* __restrict__ OUT, int out_col0) {
;     constexpr int NP = (DV / 32) * 2 / 8, NEB = DV / 32;
;     const int l31 = c.lane & 31, hi = c.lane >> 5;
;     unsigned char* QL = c.lds; unsigned char* KL = c.lds + 16384; unsigned char* VL = c.lds + 32768; unsigned char* SL = c.lds + 65536;
;     bf16* Al = (bf16*)(c.lds + 131072);
;     float* SS = (float*)(c.lds + 131072 + 9216);
;     const int eb = (c.wave * NP) >> 1;
;     const int ib1 = c.wave >> 1, jb1 = c.wave & 1;
;     f32x4 gn[4];
; #pragma unroll
;     for (int g = 0; g < 4; ++g) gn[g] = *(const f32x4*)(gain + 32 * eb + 8 * g + 4 * hi);
;     ...
;     La3Stage<DV> stg;
;     if (c.bid < 2048) la3_issue<DV>(stg, QT, KT, VT, ST, c.bid, c.tid);
;     for (int u = c.bid; u < 2048; u += c.G) {
;         const int cp = u >> 2, h = u & 3; const size_t row0 = (size_t)cp * 64;
;         la3_commit<DV>(stg, c.lds, c.tid);
;         __syncthreads();
;         if (c.wave < 4) {
;             f32x16 acc; for (int r = 0; r < 16; ++r) acc[r] = 0.f;
;             if (jb1 <= ib1) {
; #pragma unroll
;                 for (int kk = 0; kk < 8; ++kk) acc = MFMA32(LA3_F256(KL, 32 * jb1 + l31, kk), LA3_F256(QL, 32 * ib1 + l31, kk), acc);
;             }
; #pragma unroll
;             for (int g = 0; g < 4; ++g) { float v[4];
; #pragma unroll
;                 for (int x = 0; x < 4; ++x) { const int j = 32 * jb1 + 8 * g + 4 * hi + x, i = 32 * ib1 + l31; v[x] = (j <= i) ? acc[4 * g + x] : 0.f; }
;                 u32x2 w; w.x = pk2(v[0], v[1]); w.y = pk2(v[2], v[3]);
;                 *(u32x2*)(Al + (32 * ib1 + l31) * 72 + 32 * jb1 + 8 * g + 4 * hi) = w; }
.Lnb_done_3:
.LBB0_327:
	s_or_b64 exec, exec, s[0:1]
	v_readlane_b32 s0, v253, 46
	s_waitcnt lgkmcnt(0)
	v_mov_b32_e32 v0, v186
	v_readlane_b32 s1, v253, 47
	s_barrier
	s_and_b64 vcc, exec, s[0:1]
	v_readfirstlane_b32 s8, v0
	s_cbranch_vccz .LBB0_339
	s_ashr_i32 s0, s8, 6
	s_lshl_b32 s4, s0, 5
	s_ashr_i32 s5, s4, 31
	v_readlane_b32 s12, v253, 20
	s_and_b32 s1, s0, 1
	s_lshl_b64 s[4:5], s[4:5], 2
	v_readlane_b32 s16, v253, 24
	v_readlane_b32 s17, v253, 25
	s_add_u32 s4, s16, s4
	v_bfe_u32 v26, v0, 5, 1
	s_addc_u32 s5, s17, s5
	v_lshlrev_b32_e32 v28, 4, v26
	global_load_dwordx4 v[32:35], v28, s[4:5] offset:96
	global_load_dwordx4 v[36:39], v28, s[4:5] offset:64
	global_load_dwordx4 v[40:43], v28, s[4:5] offset:32
	global_load_dwordx4 v[44:47], v28, s[4:5]
	v_lshlrev_b32_e32 v1, 4, v0
	v_readlane_b32 s4, v253, 52
	v_and_b32_e32 v160, 0xf0, v1
	v_readlane_b32 s5, v253, 53
	v_ashrrev_i32_e32 v8, 4, v0
	v_ashrrev_i32_e32 v9, 31, v8
	v_lshl_add_u64 v[4:5], s[4:5], 0, v[160:161]
	v_readlane_b32 s4, v253, 54
	v_readlane_b32 s5, v253, 55
	v_lshlrev_b64 v[128:129], 9, v[8:9]
	v_ashrrev_i32_e32 v1, 31, v0
	v_lshl_add_u64 v[6:7], s[4:5], 0, v[160:161]
	v_readlane_b32 s4, v253, 48
	v_readlane_b32 s5, v253, 49
	v_lshlrev_b64 v[132:133], 4, v[0:1]
	v_add_u32_e32 v16, 0xa00, v0
	v_lshl_add_u64 v[2:3], v[128:129], 0, s[4:5]
	v_lshlrev_b64 v[2:3], 1, v[2:3]
	v_lshl_add_u64 v[10:11], v[4:5], 0, v[2:3]
	v_lshl_add_u64 v[2:3], v[6:7], 0, v[2:3]
	global_load_dwordx4 v[48:51], v[10:11], off
	global_load_dwordx4 v[52:55], v[2:3], off
	v_add_u32_e32 v2, 0x200, v0
	v_ashrrev_i32_e32 v10, 4, v2
	v_ashrrev_i32_e32 v11, 31, v10
	v_lshlrev_b64 v[130:131], 9, v[10:11]
	v_lshl_add_u64 v[12:13], v[130:131], 0, s[4:5]
	v_lshlrev_b64 v[12:13], 1, v[12:13]
	v_readlane_b32 s4, v253, 56
	v_ashrrev_i32_e32 v3, 31, v2
	v_lshl_add_u64 v[4:5], v[4:5], 0, v[12:13]
	v_lshl_add_u64 v[6:7], v[6:7], 0, v[12:13]
	v_readlane_b32 s5, v253, 57
	v_lshlrev_b64 v[134:135], 4, v[2:3]
	global_load_dwordx4 v[56:59], v[4:5], off
	global_load_dwordx4 v[60:63], v[6:7], off
	v_lshl_add_u64 v[4:5], s[4:5], 0, v[132:133]
	v_lshl_add_u64 v[6:7], s[4:5], 0, v[134:135]
	global_load_dwordx4 v[64:67], v[4:5], off
	global_load_dwordx4 v[68:71], v[6:7], off
	v_add_u32_e32 v6, 0x400, v0
	v_add_u32_e32 v4, 0x600, v0
	v_ashrrev_i32_e32 v7, 31, v6
	v_ashrrev_i32_e32 v5, 31, v4
	v_lshlrev_b64 v[136:137], 4, v[6:7]
	v_lshlrev_b64 v[138:139], 4, v[4:5]
	v_lshl_add_u64 v[12:13], s[4:5], 0, v[136:137]
	v_lshl_add_u64 v[14:15], s[4:5], 0, v[138:139]
	v_readlane_b32 s4, v253, 60
	v_readlane_b32 s5, v253, 61
	global_load_dwordx4 v[72:75], v[12:13], off
	global_load_dwordx4 v[76:79], v[14:15], off
	v_lshl_add_u64 v[12:13], s[4:5], 0, v[132:133]
	v_lshl_add_u64 v[14:15], s[4:5], 0, v[134:135]
	global_load_dwordx4 v[80:83], v[12:13], off
	global_load_dwordx4 v[84:87], v[14:15], off
	v_lshl_add_u64 v[12:13], s[4:5], 0, v[136:137]
	v_lshl_add_u64 v[14:15], s[4:5], 0, v[138:139]
	global_load_dwordx4 v[88:91], v[12:13], off
	global_load_dwordx4 v[92:95], v[14:15], off
	v_add_u32_e32 v12, 0x800, v0
	v_ashrrev_i32_e32 v13, 31, v12
	v_lshlrev_b64 v[140:141], 4, v[12:13]
	v_ashrrev_i32_e32 v17, 31, v16
	v_lshl_add_u64 v[14:15], s[4:5], 0, v[140:141]
	v_lshlrev_b64 v[142:143], 4, v[16:17]
	v_lshl_add_u64 v[18:19], s[4:5], 0, v[142:143]
	global_load_dwordx4 v[96:99], v[14:15], off
	global_load_dwordx4 v[100:103], v[18:19], off
	v_add_u32_e32 v14, 0xc00, v0
	v_ashrrev_i32_e32 v15, 31, v14
	v_add_u32_e32 v20, 0xe00, v0
	v_lshlrev_b64 v[144:145], 4, v[14:15]
	v_ashrrev_i32_e32 v21, 31, v20
	v_lshl_add_u64 v[18:19], s[4:5], 0, v[144:145]
	v_lshlrev_b64 v[146:147], 4, v[20:21]
	v_lshl_add_u64 v[22:23], s[4:5], 0, v[146:147]
	global_load_dwordx4 v[104:107], v[18:19], off
	global_load_dwordx4 v[108:111], v[22:23], off
	v_and_b32_e32 v22, 64, v193
	v_xor_b32_e32 v21, 32, v193
	v_add_u32_e32 v22, 64, v22
	v_cmp_lt_i32_e32 vcc, v21, v22
	v_and_b32_e32 v11, 15, v0
	v_lshlrev_b32_e32 v27, 2, v26
	v_cndmask_b32_e32 v21, v193, v21, vcc
	v_lshlrev_b32_e32 v206, 2, v21
	v_bitop3_b32 v21, v26, v0, 15 bitop3:0x78
	v_lshlrev_b32_e32 v208, 4, v21
	v_bitop3_b32 v21, v26, v11, 2 bitop3:0x36
	v_lshlrev_b32_e32 v209, 4, v21
	v_bitop3_b32 v21, v26, v11, 4 bitop3:0x36
	v_lshlrev_b32_e32 v210, 4, v21
	v_bitop3_b32 v21, v26, v11, 6 bitop3:0x36
	v_lshlrev_b32_e32 v211, 4, v21
	v_bitop3_b32 v21, v26, v11, 8 bitop3:0x36
	v_lshlrev_b32_e32 v212, 4, v21
	v_bitop3_b32 v21, v26, v11, 10 bitop3:0x36
	v_and_b32_e32 v25, 31, v0
	s_ashr_i32 s6, s8, 7
	v_lshl_or_b32 v13, s1, 5, v27
	v_lshlrev_b32_e32 v213, 4, v21
	v_bitop3_b32 v21, v26, v11, 12 bitop3:0x36
	v_bitop3_b32 v11, v26, v11, 14 bitop3:0x36
	v_readlane_b32 s13, v253, 21
	v_lshl_or_b32 v15, s6, 5, v25
	v_lshlrev_b32_e32 v215, 4, v11
	v_or_b32_e32 v11, 2, v13
	v_readlane_b32 s14, v253, 22
	v_readlane_b32 s15, v253, 23
	v_cmp_gt_i32_e64 s[12:13], v11, v15
	v_or_b32_e32 v11, 3, v13
	v_cmp_gt_i32_e64 s[14:15], v11, v15
	v_or_b32_e32 v11, 8, v13
	v_readlane_b32 s18, v253, 26
	v_readlane_b32 s19, v253, 27
	s_cmp_le_i32 s1, s6
	v_cmp_gt_i32_e64 s[16:17], v11, v15
	v_or_b32_e32 v11, 9, v13
	v_readlane_b32 s20, v253, 28
	v_readlane_b32 s21, v253, 29
	s_cselect_b64 s[4:5], -1, 0
	s_lshl_b32 s7, s1, 13
	v_cmp_gt_i32_e64 s[18:19], v11, v15
	v_or_b32_e32 v11, 10, v13
	v_readlane_b32 s22, v253, 30
	v_readlane_b32 s23, v253, 31
	v_lshlrev_b32_e32 v9, 8, v25
	s_add_i32 s7, s7, 0
	v_cmp_gt_i32_e64 s[20:21], v11, v15
	v_or_b32_e32 v11, 11, v13
	v_readlane_b32 s24, v253, 32
	v_readlane_b32 s25, v253, 33
	v_add_u32_e32 v202, s7, v9
	s_lshl_b32 s7, s6, 13
	s_movk_i32 s2, 0x90
	s_add_i32 s6, 0, 0x20000
	s_lshl_b32 s1, s1, 6
; template <int DV> DI void la3_commit(const La3Stage<DV>& r, unsigned char* lds, int tid) {
;     ...
;     for (int i = 0; i < 2; ++i) { const int q = tid + 512 * i, row = q >> 4, ch = q & 15; const int off = row * 256 + ((ch ^ (row & 15)) << 4);
;         *(u32x4*)(lds + off) = r.q[i]; *(u32x4*)(lds + 16384 + off) = r.k[i]; }
; #pragma unroll
;     for (int i = 0; i < DV / 64; ++i) { const int q = tid + 512 * i, row = q >> 3, ch = q & 7; *(u32x4*)(lds + 32768 + row * 128 + ((ch ^ (row & 7)) << 4)) = r.v[i]; }
; #pragma unroll
;     for (int i = 0; i < DV / 32; ++i) { const int q = tid + 512 * i, row = q >> 4, ch = q & 15; *(u32x4*)(lds + 65536 + row * 256 + ((ch ^ (row & 15)) << 4)) = r.s[i]; }
; template <int DV> DI void la3(const Ctx& c, const bf16* __restrict__ QT, const bf16* __restrict__ KT, const bf16* __restrict__ VT, const bf16* __restrict__ ST, const float* __restrict__ gain, const bf16* __restrict__ gate, int gate_ld, bf16* __restrict__ OUT, int out_col0) {
;     ...
;         if (c.wave < 4) {
;             f32x16 acc; for (int r = 0; r < 16; ++r) acc[r] = 0.f;
;             if (jb1 <= ib1) {
; #pragma unroll
;                 for (int kk = 0; kk < 8; ++kk) acc = MFMA32(LA3_F256(KL, 32 * jb1 + l31, kk), LA3_F256(QL, 32 * ib1 + l31, kk), acc);
;             }
; #pragma unroll
;             for (int g = 0; g < 4; ++g) { float v[4];
; #pragma unroll
;                 for (int x = 0; x < 4; ++x) { const int j = 32 * jb1 + 8 * g + 4 * hi + x, i = 32 * ib1 + l31; v[x] = (j <= i) ? acc[4 * g + x] : 0.f; }
;                 u32x2 w; w.x = pk2(v[0], v[1]); w.y = pk2(v[2], v[3]);
;                 *(u32x2*)(Al + (32 * ib1 + l31) * 72 + 32 * jb1 + 8 * g + 4 * hi) = w; }
;         }
;         __syncthreads();
;         u32x4 gtv[DV / 64];
; #pragma unroll
;         for (int k = 0; k < DV / 64; ++k) { const int q = c.tid + 512 * k, row = q / (DV / 8), c8 = q % (DV / 8); gtv[k] = *(const u32x4*)(gate + (row0 + row) * gate_ld + h * DV + 8 * c8); }
;         f32x16 acc[NP];
; #pragma unroll
;         for (int i = 0; i < NP; ++i) {
;             const int ib = (c.wave * NP + i) & 1;
;             for (int r = 0; r < 16; ++r) acc[i][r] = 0.f;
; #pragma unroll
;             for (int kk = 0; kk < 4; ++kk) { const bf16x8 ab = *(const bf16x8*)(Al + (32 * ib + l31) * 72 + 16 * kk + 8 * hi); acc[i] = MFMA32(LA3_F128(VL, 32 * eb + l31, kk), ab, acc[i]); }
; #pragma unroll
	v_cmp_gt_i32_e64 s[22:23], v11, v15
	v_or_b32_e32 v11, 16, v13
	v_readlane_b32 s26, v253, 34
	v_readlane_b32 s27, v253, 35
	v_mul_lo_u32 v17, v15, s2
	s_add_i32 s1, s1, s6
	v_lshlrev_b32_e32 v18, 3, v26
	v_cmp_gt_i32_e64 s[24:25], v11, v15
	v_or_b32_e32 v11, 17, v13
	v_add3_u32 v204, s1, v17, v18
	s_lshl_b32 s1, s0, 12
	v_cmp_gt_i32_e64 s[26:27], v11, v15
	v_or_b32_e32 v11, 18, v13
	s_add_i32 s1, s1, 0
	v_cmp_gt_i32_e64 s[28:29], v11, v15
	v_or_b32_e32 v11, 19, v13
	v_add_u32_e32 v17, s6, v28
	v_lshl_add_u32 v18, v25, 7, s1
	s_lshl_b32 s6, s0, 13
	s_add_i32 s1, 0, 0x10000
	s_and_b32 s42, s8, 0x3fffffc0
	v_cmp_gt_i32_e64 s[30:31], v11, v15
	v_or_b32_e32 v11, 24, v13
	v_lshrrev_b32_e32 v1, 27, v1
	s_add_i32 s7, s7, 0
	s_add_i32 s6, s1, s6
	v_cmp_gt_i32_e64 s[34:35], v11, v15
	v_or_b32_e32 v11, 25, v13
	s_lshl_b32 s42, s42, 2
	v_readlane_b32 s2, v254, 44
	v_add_u32_e32 v1, v0, v1
	v_and_b32_e32 v24, 63, v0
	v_add_u32_e32 v203, s7, v9
	v_add_u32_e32 v205, s6, v9
	v_cmp_gt_i32_e64 s[36:37], v11, v15
	v_or_b32_e32 v11, 26, v13
	v_add_u32_e32 v216, 0, v9
	s_add_i32 s42, s2, s42
	v_or_b32_e32 v9, 32, v25
	v_ashrrev_i32_e32 v27, 3, v0
	v_ashrrev_i32_e32 v29, 3, v2
	v_ashrrev_i32_e32 v31, 3, v6
	v_ashrrev_i32_e32 v113, 3, v4
	v_ashrrev_i32_e32 v115, 4, v6
	v_ashrrev_i32_e32 v118, 4, v4
	v_ashrrev_i32_e32 v12, 4, v12
	v_ashrrev_i32_e32 v16, 4, v16
	v_ashrrev_i32_e32 v14, 4, v14
	v_ashrrev_i32_e32 v20, 4, v20
	v_ashrrev_i32_e32 v148, 5, v1
	v_and_b32_e32 v1, 0xffffffe0, v1
	v_and_b32_e32 v19, 7, v0
	v_cmp_gt_u32_e64 s[6:7], 32, v24
	v_lshl_or_b32 v207, s0, 7, v28
	v_cmp_gt_i32_e64 s[8:9], v13, v15
	v_cmp_lt_i32_e64 s[10:11], v13, v15
	v_cmp_gt_i32_e64 s[38:39], v11, v15
	v_or_b32_e32 v11, 27, v13
	v_bitop3_b32 v13, v26, v0, 7 bitop3:0x78
	v_lshl_add_u32 v217, v24, 2, s42
	v_mul_u32_u24_e32 v22, 0x90, v9
	v_lshl_add_u32 v219, v9, 2, s2
	v_lshlrev_b32_e32 v9, 8, v8
	v_xor_b32_e32 v8, v8, v0
	v_lshlrev_b32_e32 v24, 8, v10
	v_xor_b32_e32 v10, v10, v0
	v_lshl_add_u32 v28, v27, 7, 0
	v_xor_b32_e32 v27, v27, v0
	v_lshl_add_u32 v30, v29, 7, 0
	v_xor_b32_e32 v29, v29, v0
	v_lshl_add_u32 v112, v31, 7, 0
	v_xor_b32_e32 v31, v31, v0
	v_lshl_add_u32 v114, v113, 7, 0
	v_xor_b32_e32 v113, v113, v0
	v_lshl_add_u32 v117, v115, 8, s1
	v_xor_b32_e32 v115, v115, v0
	v_lshl_add_u32 v119, v118, 8, s1
	v_xor_b32_e32 v118, v118, v0
	v_lshl_add_u32 v120, v12, 8, s1
	v_xor_b32_e32 v12, v12, v0
	v_lshl_add_u32 v121, v16, 8, s1
	v_xor_b32_e32 v16, v16, v0
	v_lshl_add_u32 v122, v14, 8, s1
	v_xor_b32_e32 v14, v14, v0
	v_lshl_add_u32 v123, v20, 8, s1
	v_xor_b32_e32 v20, v20, v0
	v_sub_u32_e32 v0, v0, v1
	v_lshrrev_b32_e32 v1, 27, v3
	v_add_u32_e32 v1, v2, v1
	v_ashrrev_i32_e32 v152, 5, v1
	v_and_b32_e32 v1, 0xffffffe0, v1
	v_sub_u32_e32 v1, v2, v1
	v_lshrrev_b32_e32 v2, 27, v7
	v_lshrrev_b32_e32 v3, 27, v5
	v_add_u32_e32 v2, v6, v2
	v_add_u32_e32 v3, v4, v3
	v_lshlrev_b32_e32 v8, 4, v8
	v_lshlrev_b32_e32 v10, 4, v10
	v_mov_b32_e32 v116, s1
	s_cmp_lt_i32 s0, 4
	v_ashrrev_i32_e32 v156, 5, v2
	v_and_b32_e32 v2, 0xffffffe0, v2
	v_ashrrev_i32_e32 v170, 5, v3
	v_and_b32_e32 v3, 0xffffffe0, v3
	s_movk_i32 s0, 0x410
	v_lshlrev_b32_e32 v214, 4, v21
	v_cmp_gt_i32_e64 s[40:41], v11, v15
	v_mul_u32_u24_e32 v11, 0x90, v25
	v_bitop3_b32 v15, v26, v19, 2 bitop3:0x36
	v_bitop3_b32 v21, v26, v19, 4 bitop3:0x36
	v_bitop3_b32 v19, v26, v19, 6 bitop3:0x36
	v_lshl_add_u32 v218, v25, 2, s2
	v_and_b32_e32 v8, 0xf0, v8
	v_and_b32_e32 v10, 0xf0, v10
	v_lshlrev_b32_e32 v27, 4, v27
	v_lshlrev_b32_e32 v29, 4, v29
	v_lshlrev_b32_e32 v31, 4, v31
	v_lshlrev_b32_e32 v113, 4, v113
	v_lshlrev_b32_e32 v115, 4, v115
	v_lshlrev_b32_e32 v118, 4, v118
	v_lshlrev_b32_e32 v12, 4, v12
	v_lshlrev_b32_e32 v16, 4, v16
	v_lshlrev_b32_e32 v14, 4, v14
	v_lshlrev_b32_e32 v20, 4, v20
	v_sub_u32_e32 v2, v6, v2
	v_sub_u32_e32 v3, v4, v3
	v_lshl_add_u64 v[174:175], s[60:61], 0, v[160:161]
	v_lshl_add_u64 v[176:177], s[94:95], 0, v[160:161]
	v_mad_u32_u24 v160, v25, s0, v116
	v_mul_lo_u32 v5, v148, s0
	v_mul_lo_u32 v6, v152, s0
	v_mul_lo_u32 v7, v156, s0
	v_mul_lo_u32 v25, v170, s0
	v_lshlrev_b32_e32 v13, 4, v13
	v_lshlrev_b32_e32 v15, 4, v15
	v_lshlrev_b32_e32 v21, 4, v21
	v_lshlrev_b32_e32 v19, 4, v19
	v_or_b32_e32 v23, v8, v9
	v_or_b32_e32 v26, v10, v24
	v_and_b32_e32 v27, 0x70, v27
	v_and_b32_e32 v29, 0x70, v29
	v_and_b32_e32 v31, 0x70, v31
	v_and_b32_e32 v113, 0x70, v113
	v_add_u32_e32 v9, s1, v9
	v_add_u32_e32 v24, s1, v24
	v_and_b32_e32 v115, 0xf0, v115
	v_and_b32_e32 v118, 0xf0, v118
	v_and_b32_e32 v12, 0xf0, v12
	v_and_b32_e32 v16, 0xf0, v16
	v_and_b32_e32 v14, 0xf0, v14
	v_and_b32_e32 v20, 0xf0, v20
	v_lshlrev_b32_e32 v150, 3, v0
	v_lshlrev_b32_e32 v154, 3, v1
	v_lshlrev_b32_e32 v158, 3, v2
	v_lshlrev_b32_e32 v172, 3, v3
	v_add_u32_e32 v4, 0x8200, v160
	v_add_u32_e32 v5, s1, v5
	v_lshlrev_b32_e32 v0, 5, v0
	v_add_u32_e32 v6, s1, v6
	v_lshlrev_b32_e32 v1, 5, v1
	v_add_u32_e32 v7, s1, v7
	v_lshlrev_b32_e32 v2, 5, v2
	v_add_u32_e32 v25, s1, v25
	v_lshlrev_b32_e32 v3, 5, v3
	s_cselect_b64 s[74:75], -1, 0
	v_ashrrev_i32_e32 v149, 31, v148
	v_ashrrev_i32_e32 v151, 31, v150
	v_ashrrev_i32_e32 v153, 31, v152
	v_ashrrev_i32_e32 v155, 31, v154
	v_ashrrev_i32_e32 v157, 31, v156
	v_ashrrev_i32_e32 v159, 31, v158
	v_ashrrev_i32_e32 v171, 31, v170
	v_ashrrev_i32_e32 v173, 31, v172
	s_lshl_b32 s67, s66, 8
	v_add_u32_e32 v220, 0, v23
	v_add_u32_e32 v221, 0, v26
	v_add_u32_e32 v222, v28, v27
	v_add_u32_e32 v223, v30, v29
	v_add_u32_e32 v224, v112, v31
	v_add_u32_e32 v225, v114, v113
	v_add_u32_e32 v226, v9, v8
	v_add_u32_e32 v227, v24, v10
	v_add_u32_e32 v228, v117, v115
	v_add_u32_e32 v229, v119, v118
	v_add_u32_e32 v230, v120, v12
	v_add_u32_e32 v231, v121, v16
	v_add_u32_e32 v232, v122, v14
	v_add_u32_e32 v233, v123, v20
	v_add_u32_e32 v234, v17, v11
	v_add_u32_e32 v235, v17, v22
	v_add_u32_e32 v236, v4, v207
	v_add_u32_e32 v237, v5, v0
	v_add_u32_e32 v238, v6, v1
	v_add_u32_e32 v239, v7, v2
	v_add_u32_e32 v240, v25, v3
	v_add_u32_e32 v241, v18, v13
	v_add_u32_e32 v242, v18, v15
	v_add_u32_e32 v243, v18, v21
	v_add_u32_e32 v244, v18, v19
	v_readlane_b32 s80, v253, 51
	s_mov_b32 s86, s90
	s_branch .LBB0_330

; #define REP(bit) for (int rep_ = 0; rep_ < (((DUP) & (bit)) ? 2 : 1); ++rep_)
; #define GSYNC() do { XcdBarrier b_; b_.bar = (unsigned*)args.ws; b_.x = xb_xcc_id(); b_.st = (volatile LAS unsigned*)((LAS unsigned char*)lds + LDS_BYTES - 64) + 8; xcd_barrier(b_); if constexpr ((DUP) & 0x10000) xcd_barrier(b_); } while (0)
; #define GEMM_PHASE(EPI_T, E, A_, Bt_, nM_, nN_, K_, AM) do { pg8::Gemm g{(const pg8::bf16_t*)(A_), (const pg8::bf16_t*)(Bt_), M, (nN_) * 256, (K_)}; pg8::StaticOrder S; S.init2((nM_), (nN_), (int)gridDim.x, (int)blockIdx.x); \
;         pg8::gemm_phase<EPI_T, pg8::StaticOrder, true, true, AM>(ldsl, g, S, E); } while (0)
; __global__ void __launch_bounds__(NTHR, 2) fwd_megakernel(Args args) {
;     ...
;             GSYNC();
;         }
;         if constexpr (PH & 128) REP(128) { pg8::EpiRes E{even ? args.in[0] : (const float*)H, H, 1024, ((DUP) & 128) && rep_ == 0 ? zopq : 1.f}; GEMM_PHASE(pg8::EpiRes, E, OUTB, ws + (even ? WS_WOUTE : WS_WOUTO), 128, 4, 1024, 0); }
.Lnb_done_4:
.LBB0_392:
	s_or_b64 exec, exec, s[0:1]
	v_readlane_b32 s8, v253, 0
	v_readlane_b32 s10, v253, 2
	v_readlane_b32 s11, v253, 3
	s_mov_b64 s[6:7], 0
	s_mov_b64 s[0:1], s[10:11]
	s_mov_b64 s[66:67], 0x1000
	s_waitcnt lgkmcnt(0)
	s_barrier
	v_readlane_b32 s9, v253, 1

; #define MFMA32(a, b, c) __builtin_amdgcn_mfma_f32_32x32x16_bf16((a), (b), (c), 0, 0, 0)
; DI void sb_attention(const Ctx& c, const bf16* Qn, const bf16* Kn, const bf16* Vv, bf16* OUT) {
;     const int l31 = c.lane & 31, hi = c.lane >> 5;
;     bf16* vl = (bf16*)(c.lds + 32768 + c.wave * 8192);
;     for (int u = c.gw; u < 8192; u += c.NGW) {
;         const int qb = u & 511, h = (u >> 9) & 7, b = u >> 12;
;         const size_t row0 = (size_t)b * SEQ + 32 * qb;
;         bf16x8 qf[4];
; #pragma unroll
;         for (int kk = 0; kk < 4; ++kk) qf[kk] = *(const bf16x8*)(Qn + (row0 + l31) * 512 + 64 * h + 16 * kk + 8 * hi);
;         float R2 = 0.f;
;         f32x16 O0, O1; for (int r = 0; r < 16; ++r) { O0[r] = 0.f; O1[r] = 0.f; }
;         bf16x8 kfn[4]; u32x4 vn[4];
;         { const size_t krow0 = (size_t)b * SEQ + 32 * qb;
; #pragma unroll
;           for (int i = 0; i < 4; ++i) { const int idx = c.lane + 64 * i, key = idx >> 3, c8 = idx & 7; vn[i] = *(const u32x4*)(Vv + (krow0 + key) * 512 + 64 * h + 8 * c8); }
; #pragma unroll
;           for (int kk = 0; kk < 4; ++kk) kfn[kk] = *(const bf16x8*)(Kn + (krow0 + l31) * 512 + 64 * h + 16 * kk + 8 * hi); }
;     ...
;             bf16x8 kf[4]; u32x4 vv[4];
; #pragma unroll
;             for (int i = 0; i < 4; ++i) { kf[i] = kfn[i]; vv[i] = vn[i]; }
;             if (kt > 0) {
;                 const size_t krow1 = (size_t)b * SEQ + 32 * (kt - 1);
; #pragma unroll
;                 for (int i = 0; i < 4; ++i) { const int idx = c.lane + 64 * i, key = idx >> 3, c8 = idx & 7; vn[i] = *(const u32x4*)(Vv + (krow1 + key) * 512 + 64 * h + 8 * c8); }
; #pragma unroll
;                 for (int kk = 0; kk < 4; ++kk) kfn[kk] = *(const bf16x8*)(Kn + (krow1 + l31) * 512 + 64 * h + 16 * kk + 8 * hi);
;             }
;             __builtin_amdgcn_fence(__ATOMIC_RELEASE, "wavefront"); __builtin_amdgcn_wave_barrier();
; #pragma unroll
;             for (int i = 0; i < 4; ++i) { const int idx = c.lane + 64 * i, key = idx >> 3, c8 = idx & 7; *(u32x4*)(vl + key * 72 + 8 * c8) = vv[i]; }
;             f32x16 s; for (int r = 0; r < 16; ++r) s[r] = 0.f;
; #pragma unroll
;             for (int kk = 0; kk < 4; ++kk) s = MFMA32(kf[kk], qf[kk], s);
;             const bool diag = (kt == qb);
;             float sp[16], lb[16];
; #pragma unroll
.Lnb_done_5:
.LBB0_521:
	s_or_b64 exec, exec, s[0:1]
	s_waitcnt lgkmcnt(0)
	v_mov_b32_e32 v0, v186
	s_barrier
	s_nop 0
	v_readfirstlane_b32 s0, v0
	s_ashr_i32 s1, s0, 6
	s_add_i32 s40, s1, s72
	s_cmpk_lt_i32 s40, 0x2000
	s_cbranch_scc0 .LBB0_532
	v_and_b32_e32 v6, 64, v193
	v_xor_b32_e32 v5, 32, v193
	v_add_u32_e32 v6, 64, v6
	v_bfe_u32 v3, v0, 5, 1
	v_cmp_lt_i32_e32 vcc, v5, v6
	v_lshlrev_b32_e32 v4, 2, v3
	v_and_b32_e32 v112, 31, v0
	v_cndmask_b32_e32 v5, v193, v5, vcc
	v_lshlrev_b32_e32 v113, 2, v5
	v_or_b32_e32 v5, 2, v4
	v_cmp_lt_u32_e64 s[10:11], v5, v112
	v_or_b32_e32 v5, 3, v4
	v_cmp_lt_u32_e64 s[12:13], v5, v112
	v_or_b32_e32 v5, 8, v4
	v_cmp_lt_u32_e64 s[14:15], v5, v112
	v_or_b32_e32 v5, 9, v4
	v_cmp_lt_u32_e64 s[16:17], v5, v112
	v_or_b32_e32 v5, 10, v4
	v_cmp_lt_u32_e64 s[18:19], v5, v112
	v_or_b32_e32 v5, 11, v4
	v_cmp_lt_u32_e64 s[20:21], v5, v112
	v_or_b32_e32 v5, 16, v4
	v_cmp_lt_u32_e64 s[22:23], v5, v112
	v_or_b32_e32 v5, 17, v4
	v_cmp_lt_u32_e64 s[24:25], v5, v112
	v_or_b32_e32 v5, 18, v4
	v_cmp_lt_u32_e64 s[26:27], v5, v112
	v_or_b32_e32 v5, 19, v4
	v_cmp_lt_u32_e64 s[28:29], v5, v112
	v_or_b32_e32 v5, 24, v4
	v_and_b32_e32 v1, 63, v0
	v_cmp_lt_u32_e64 s[30:31], v5, v112
	v_or_b32_e32 v5, 25, v4
	v_cmp_gt_u32_e64 s[4:5], 32, v1
	v_or_b32_e32 v1, 1, v4
	v_cmp_lt_u32_e64 s[34:35], v5, v112
	v_or_b32_e32 v5, 26, v4
	s_lshl_b32 s1, s1, 13
	v_cmp_lt_u32_e64 s[8:9], v1, v112
	v_cmp_lt_u32_e64 s[36:37], v5, v112
	v_or_b32_e32 v5, 27, v4
	v_mul_u32_u24_e32 v1, 0x48, v1
	s_add_i32 s1, s1, 0
	v_cmp_lt_u32_e64 s[38:39], v5, v112
	v_lshlrev_b32_e32 v5, 1, v112
	v_lshlrev_b32_e32 v1, 1, v1
	v_lshlrev_b32_e32 v160, 4, v3
	v_add3_u32 v121, s1, v1, v5
	v_lshlrev_b32_e32 v1, 4, v0
	v_bfe_u32 v118, v0, 3, 3
	v_lshlrev_b32_e32 v2, 3, v3
	v_lshl_add_u64 v[114:115], s[94:95], 0, v[160:161]
	v_mul_u32_u24_e32 v3, 0x120, v3
	v_and_b32_e32 v160, 0x70, v1
	v_mul_u32_u24_e32 v0, 0x90, v118
	s_lshr_b32 s0, s0, 6
	v_lshlrev_b32_e32 v3, 1, v3
	v_add3_u32 v139, s1, v0, v160
	s_lshl_b32 s41, s42, 3
	v_cmp_lt_u32_e64 s[6:7], v4, v112
	v_add3_u32 v119, s1, v3, v5
	v_add_u32_e32 v123, 0x90, v121
	v_add_u32_e32 v125, 0x120, v121
	v_add_u32_e32 v136, 0x3f0, v121
	v_add_u32_e32 v137, 0x870, v121
	v_add_u32_e32 v138, 0xcf0, v121
	v_lshl_add_u64 v[116:117], s[78:79], 0, v[160:161]
	v_or_b32_e32 v120, 8, v118
	v_or_b32_e32 v122, 16, v118
	v_or_b32_e32 v124, 24, v118
	v_add_u32_e32 v140, 0x480, v139
	v_add_u32_e32 v141, 0x900, v139
	v_add_u32_e32 v142, 0xd80, v139
	s_add_i32 s43, s72, s0
	v_lshlrev_b32_e32 v126, 1, v2
	v_lshlrev_b32_e32 v128, 1, v4
	s_branch .LBB0_524

; template <int DV> DI void la3_issue(La3Stage<DV>& r, const bf16* __restrict__ QT, const bf16* __restrict__ KT, const bf16* __restrict__ VT, const bf16* __restrict__ ST, int u, int tid) {
;     const int cp = u >> 2, h = u & 3; const size_t row0 = (size_t)cp * 64;
; #pragma unroll
;     for (int i = 0; i < 2; ++i) { const int q = tid + 512 * i, row = q >> 4, ch = q & 15;
;         r.q[i] = *(const u32x4*)(QT + (row0 + row) * 512 + h * 128 + ch * 8); r.k[i] = *(const u32x4*)(KT + (row0 + row) * 512 + h * 128 + ch * 8); }
; template <int DV> DI void la3(const Ctx& c, const bf16* __restrict__ QT, const bf16* __restrict__ KT, const bf16* __restrict__ VT, const bf16* __restrict__ ST, const float* __restrict__ gain, const bf16* __restrict__ gate, int gate_ld, bf16* __restrict__ OUT, int out_col0) {
;     constexpr int NP = (DV / 32) * 2 / 8, NEB = DV / 32;
;     const int l31 = c.lane & 31, hi = c.lane >> 5;
;     unsigned char* QL = c.lds; unsigned char* KL = c.lds + 16384; unsigned char* VL = c.lds + 32768; unsigned char* SL = c.lds + 65536;
;     bf16* Al = (bf16*)(c.lds + 131072);
;     float* SS = (float*)(c.lds + 131072 + 9216);
;     const int eb = (c.wave * NP) >> 1;
;     const int ib1 = c.wave >> 1, jb1 = c.wave & 1;
;     f32x4 gn[4];
; #pragma unroll
;     for (int g = 0; g < 4; ++g) gn[g] = *(const f32x4*)(gain + 32 * eb + 8 * g + 4 * hi);
;     ...
;     La3Stage<DV> stg;
;     if (c.bid < 2048) la3_issue<DV>(stg, QT, KT, VT, ST, c.bid, c.tid);
;     for (int u = c.bid; u < 2048; u += c.G) {
;         const int cp = u >> 2, h = u & 3; const size_t row0 = (size_t)cp * 64;
;         la3_commit<DV>(stg, c.lds, c.tid);
;         __syncthreads();
;         if (c.wave < 4) {
;             f32x16 acc; for (int r = 0; r < 16; ++r) acc[r] = 0.f;
;             if (jb1 <= ib1) {
; #pragma unroll
;                 for (int kk = 0; kk < 8; ++kk) acc = MFMA32(LA3_F256(KL, 32 * jb1 + l31, kk), LA3_F256(QL, 32 * ib1 + l31, kk), acc);
;             }
; #pragma unroll
;             for (int g = 0; g < 4; ++g) { float v[4];
; #pragma unroll
;                 for (int x = 0; x < 4; ++x) { const int j = 32 * jb1 + 8 * g + 4 * hi + x, i = 32 * ib1 + l31; v[x] = (j <= i) ? acc[4 * g + x] : 0.f; }
;                 u32x2 w; w.x = pk2(v[0], v[1]); w.y = pk2(v[2], v[3]);
;                 *(u32x2*)(Al + (32 * ib1 + l31) * 72 + 32 * jb1 + 8 * g + 4 * hi) = w; }
.Lnb_done_6:
.LBB0_596:
	s_or_b64 exec, exec, s[0:1]
	v_readlane_b32 s0, v253, 46
	s_waitcnt lgkmcnt(0)
	v_mov_b32_e32 v0, v186
	v_readlane_b32 s1, v253, 47
	s_barrier
	s_and_b64 vcc, exec, s[0:1]
	v_readfirstlane_b32 s6, v0
	s_cbranch_vccz .LBB0_606
	s_ashr_i32 s0, s6, 7
	s_lshl_b32 s4, s0, 5
	s_ashr_i32 s40, s6, 6
	s_ashr_i32 s5, s4, 31
	v_readlane_b32 s12, v253, 4
	s_and_b32 s1, s40, 1
	s_lshl_b64 s[8:9], s[4:5], 2
	v_readlane_b32 s22, v253, 14
	v_readlane_b32 s23, v253, 15
	s_add_u32 s8, s22, s8
	s_waitcnt vmcnt(13)
	v_bfe_u32 v74, v0, 5, 1
	s_addc_u32 s9, s23, s9
	v_lshlrev_b32_e32 v75, 4, v74
	global_load_dwordx4 v[16:19], v75, s[8:9] offset:96
	global_load_dwordx4 v[20:23], v75, s[8:9] offset:64
	global_load_dwordx4 v[24:27], v75, s[8:9] offset:32
	global_load_dwordx4 v[28:31], v75, s[8:9]
	v_lshlrev_b32_e32 v1, 4, v0
	v_readlane_b32 s8, v254, 0
	v_and_b32_e32 v160, 0xf0, v1
	v_readlane_b32 s9, v254, 1
	v_ashrrev_i32_e32 v6, 4, v0
	v_ashrrev_i32_e32 v7, 31, v6
	v_lshl_add_u64 v[2:3], s[8:9], 0, v[160:161]
	v_readlane_b32 s8, v254, 2
	v_readlane_b32 s9, v254, 3
	s_waitcnt vmcnt(15)
	v_lshlrev_b64 v[80:81], 9, v[6:7]
	v_ashrrev_i32_e32 v1, 31, v0
	v_lshl_add_u64 v[4:5], s[8:9], 0, v[160:161]
	v_readlane_b32 s8, v253, 48
	v_readlane_b32 s9, v253, 49
	s_waitcnt vmcnt(14)
	v_lshlrev_b64 v[84:85], 4, v[0:1]
	v_and_b32_e32 v72, 31, v0
	v_lshl_add_u64 v[8:9], v[80:81], 0, s[8:9]
	v_lshlrev_b64 v[8:9], 1, v[8:9]
	v_lshl_add_u64 v[10:11], v[2:3], 0, v[8:9]
	v_lshl_add_u64 v[8:9], v[4:5], 0, v[8:9]
	global_load_dwordx4 v[32:35], v[10:11], off
	global_load_dwordx4 v[36:39], v[8:9], off
	v_add_u32_e32 v8, 0x200, v0
	v_ashrrev_i32_e32 v10, 4, v8
	v_ashrrev_i32_e32 v11, 31, v10
	v_lshlrev_b64 v[82:83], 9, v[10:11]
	v_lshl_add_u64 v[12:13], v[82:83], 0, s[8:9]
	v_lshlrev_b64 v[12:13], 1, v[12:13]
	v_readlane_b32 s8, v254, 4
	v_ashrrev_i32_e32 v9, 31, v8
	v_lshl_add_u64 v[2:3], v[2:3], 0, v[12:13]
	v_lshl_add_u64 v[4:5], v[4:5], 0, v[12:13]
	v_readlane_b32 s9, v254, 5
	v_lshlrev_b64 v[86:87], 4, v[8:9]
	global_load_dwordx4 v[40:43], v[2:3], off
	global_load_dwordx4 v[44:47], v[4:5], off
	v_lshl_add_u64 v[2:3], s[8:9], 0, v[84:85]
	v_lshl_add_u64 v[4:5], s[8:9], 0, v[86:87]
	v_readlane_b32 s8, v254, 8
	v_readlane_b32 s9, v254, 9
	global_load_dwordx4 v[48:51], v[2:3], off
	global_load_dwordx4 v[52:55], v[4:5], off
	v_lshl_add_u64 v[2:3], s[8:9], 0, v[84:85]
	v_lshl_add_u64 v[4:5], s[8:9], 0, v[86:87]
	global_load_dwordx4 v[56:59], v[2:3], off
	global_load_dwordx4 v[60:63], v[4:5], off
	v_add_u32_e32 v2, 0x400, v0
	v_ashrrev_i32_e32 v3, 31, v2
	v_add_u32_e32 v12, 0x600, v0
	s_waitcnt vmcnt(21)
	v_lshlrev_b64 v[88:89], 4, v[2:3]
	v_ashrrev_i32_e32 v13, 31, v12
	v_lshl_add_u64 v[4:5], s[8:9], 0, v[88:89]
	v_lshlrev_b64 v[90:91], 4, v[12:13]
	v_lshl_add_u64 v[14:15], s[8:9], 0, v[90:91]
	global_load_dwordx4 v[64:67], v[4:5], off
	global_load_dwordx4 v[68:71], v[14:15], off
	s_cmp_le_i32 s1, s0
	v_lshlrev_b32_e32 v3, 8, v72
	s_cselect_b64 s[74:75], -1, 0
	v_lshl_or_b32 v4, s1, 13, v3
	v_lshl_or_b32 v3, s0, 13, v3
	s_add_i32 s43, 0, 0x10000
	v_and_b32_e32 v15, 64, v193
	s_waitcnt vmcnt(18)
; template <int DV> DI void la3_commit(const La3Stage<DV>& r, unsigned char* lds, int tid) {
;     ...
;     for (int i = 0; i < 2; ++i) { const int q = tid + 512 * i, row = q >> 4, ch = q & 15; const int off = row * 256 + ((ch ^ (row & 15)) << 4);
;         *(u32x4*)(lds + off) = r.q[i]; *(u32x4*)(lds + 16384 + off) = r.k[i]; }
; #pragma unroll
;     for (int i = 0; i < DV / 64; ++i) { const int q = tid + 512 * i, row = q >> 3, ch = q & 7; *(u32x4*)(lds + 32768 + row * 128 + ((ch ^ (row & 7)) << 4)) = r.v[i]; }
; #pragma unroll
;     for (int i = 0; i < DV / 32; ++i) { const int q = tid + 512 * i, row = q >> 4, ch = q & 15; *(u32x4*)(lds + 65536 + row * 256 + ((ch ^ (row & 15)) << 4)) = r.s[i]; }
; template <int DV> DI void la3(const Ctx& c, const bf16* __restrict__ QT, const bf16* __restrict__ KT, const bf16* __restrict__ VT, const bf16* __restrict__ ST, const float* __restrict__ gain, const bf16* __restrict__ gate, int gate_ld, bf16* __restrict__ OUT, int out_col0) {
;     ...
;         if (c.wave < 4) {
;             f32x16 acc; for (int r = 0; r < 16; ++r) acc[r] = 0.f;
;             if (jb1 <= ib1) {
; #pragma unroll
;                 for (int kk = 0; kk < 8; ++kk) acc = MFMA32(LA3_F256(KL, 32 * jb1 + l31, kk), LA3_F256(QL, 32 * ib1 + l31, kk), acc);
;             }
; #pragma unroll
;             for (int g = 0; g < 4; ++g) { float v[4];
; #pragma unroll
;                 for (int x = 0; x < 4; ++x) { const int j = 32 * jb1 + 8 * g + 4 * hi + x, i = 32 * ib1 + l31; v[x] = (j <= i) ? acc[4 * g + x] : 0.f; }
;                 u32x2 w; w.x = pk2(v[0], v[1]); w.y = pk2(v[2], v[3]);
;                 *(u32x2*)(Al + (32 * ib1 + l31) * 72 + 32 * jb1 + 8 * g + 4 * hi) = w; }
;         }
;         __syncthreads();
;         u32x4 gtv[DV / 64];
; #pragma unroll
;         for (int k = 0; k < DV / 64; ++k) { const int q = c.tid + 512 * k, row = q / (DV / 8), c8 = q % (DV / 8); gtv[k] = *(const u32x4*)(gate + (row0 + row) * gate_ld + h * DV + 8 * c8); }
;         f32x16 acc[NP];
; #pragma unroll
;         for (int i = 0; i < NP; ++i) {
;             const int ib = (c.wave * NP + i) & 1;
;             for (int r = 0; r < 16; ++r) acc[i][r] = 0.f;
; #pragma unroll
;             for (int kk = 0; kk < 4; ++kk) { const bf16x8 ab = *(const bf16x8*)(Al + (32 * ib + l31) * 72 + 16 * kk + 8 * hi); acc[i] = MFMA32(LA3_F128(VL, 32 * eb + l31, kk), ab, acc[i]); }
; #pragma unroll
	v_add_u32_e32 v109, 0, v3
	v_add_u32_e32 v111, s43, v3
	v_xor_b32_e32 v3, 32, v193
	v_add_u32_e32 v15, 64, v15
	v_cmp_lt_i32_e32 vcc, v3, v15
	v_add_u32_e32 v108, 0, v4
	v_and_b32_e32 v4, 15, v0
	v_cndmask_b32_e32 v3, v193, v3, vcc
	v_lshlrev_b32_e32 v112, 2, v3
	v_bitop3_b32 v3, v74, v0, 15 bitop3:0x78
	v_lshlrev_b32_e32 v113, 4, v3
	v_bitop3_b32 v3, v74, v4, 2 bitop3:0x36
	v_lshlrev_b32_e32 v114, 4, v3
	v_bitop3_b32 v3, v74, v4, 4 bitop3:0x36
	v_lshlrev_b32_e32 v115, 4, v3
	v_bitop3_b32 v3, v74, v4, 6 bitop3:0x36
	v_lshlrev_b32_e32 v116, 4, v3
	v_bitop3_b32 v3, v74, v4, 8 bitop3:0x36
	v_lshlrev_b32_e32 v117, 4, v3
	v_bitop3_b32 v3, v74, v4, 10 bitop3:0x36
	s_lshl_b32 s41, s1, 5
	v_lshlrev_b32_e32 v118, 4, v3
	v_bitop3_b32 v3, v74, v4, 12 bitop3:0x36
	v_lshl_or_b32 v5, v74, 2, s41
	v_lshlrev_b32_e32 v119, 4, v3
	v_bitop3_b32 v3, v74, v4, 14 bitop3:0x36
	v_or_b32_e32 v7, s4, v72
	v_lshlrev_b32_e32 v120, 4, v3
	v_or_b32_e32 v3, 2, v5
	v_readlane_b32 s13, v253, 5
	v_cmp_gt_i32_e64 s[10:11], v3, v7
	v_or_b32_e32 v3, 3, v5
	v_readlane_b32 s14, v253, 6
	v_readlane_b32 s15, v253, 7
	v_cmp_gt_i32_e64 s[12:13], v3, v7
	v_or_b32_e32 v3, 8, v5
	v_readlane_b32 s16, v253, 8
	v_readlane_b32 s17, v253, 9
	v_cmp_gt_i32_e64 s[14:15], v3, v7
	v_or_b32_e32 v3, 9, v5
	v_readlane_b32 s18, v253, 10
	v_readlane_b32 s19, v253, 11
	v_cmp_gt_i32_e64 s[16:17], v3, v7
	v_or_b32_e32 v3, 10, v5
	v_readlane_b32 s20, v253, 12
	v_readlane_b32 s21, v253, 13
	v_cmp_gt_i32_e64 s[18:19], v3, v7
	v_or_b32_e32 v3, 11, v5
	v_cmp_gt_i32_e64 s[20:21], v3, v7
	v_or_b32_e32 v3, 16, v5
	v_readlane_b32 s24, v253, 16
	v_readlane_b32 s25, v253, 17
	v_cmp_gt_i32_e64 s[22:23], v3, v7
	v_or_b32_e32 v3, 17, v5
	v_readlane_b32 s26, v253, 18
	v_readlane_b32 s27, v253, 19
	v_cmp_gt_i32_e64 s[24:25], v3, v7
	v_or_b32_e32 v3, 18, v5
	s_movk_i32 s2, 0x90
	s_add_i32 s4, 0, 0x20000
	s_lshl_b32 s5, s1, 6
	v_cmp_gt_i32_e64 s[26:27], v3, v7
	v_or_b32_e32 v3, 19, v5
	v_mul_lo_u32 v11, v7, s2
	s_add_i32 s5, s5, s4
	v_lshlrev_b32_e32 v13, 3, v74
	v_cmp_gt_i32_e64 s[28:29], v3, v7
	v_or_b32_e32 v3, 24, v5
	v_add3_u32 v110, s5, v11, v13
	v_add_u32_e32 v11, s4, v75
	s_lshl_b32 s4, s0, 12
	v_cmp_gt_i32_e64 s[30:31], v3, v7
	v_or_b32_e32 v3, 25, v5
	v_lshrrev_b32_e32 v1, 28, v1
	s_add_i32 s4, s4, 0
	s_and_b32 s52, s6, 0xffffff80
	v_cmp_gt_i32_e64 s[34:35], v3, v7
	v_or_b32_e32 v3, 26, v5
	v_add_u32_e32 v1, v0, v1
	v_and_b32_e32 v14, 7, v0
	v_cmp_gt_i32_e64 s[36:37], v3, v7
	v_or_b32_e32 v3, 27, v5
	v_ashrrev_i32_e32 v77, 3, v0
	v_ashrrev_i32_e32 v79, 3, v8
	v_ashrrev_i32_e32 v2, 4, v2
	v_ashrrev_i32_e32 v12, 4, v12
	s_cmp_lt_i32 s40, 4
	v_ashrrev_i32_e32 v92, 4, v1
	v_and_b32_e32 v1, -16, v1
	v_and_b32_e32 v73, 63, v0
	v_cmp_gt_i32_e64 s[6:7], v5, v7
	v_cmp_lt_i32_e64 s[8:9], v5, v7
	v_cmp_gt_i32_e64 s[38:39], v3, v7
	v_bitop3_b32 v3, v74, v0, 7 bitop3:0x78
	v_bitop3_b32 v4, v74, v14, 2 bitop3:0x36
	v_bitop3_b32 v5, v74, v14, 4 bitop3:0x36
	v_bitop3_b32 v7, v74, v14, 6 bitop3:0x36
	v_lshlrev_b32_e32 v14, 8, v6
	v_xor_b32_e32 v6, v6, v0
	v_lshlrev_b32_e32 v74, 8, v10
	v_xor_b32_e32 v10, v10, v0
	v_lshl_add_u32 v78, v77, 7, 0
	v_xor_b32_e32 v77, v77, v0
	v_lshl_add_u32 v104, v79, 7, 0
	v_xor_b32_e32 v79, v79, v0
	v_lshl_add_u32 v105, v2, 8, s43
	v_xor_b32_e32 v2, v2, v0
	v_lshl_add_u32 v106, v12, 8, s43
	v_xor_b32_e32 v12, v12, v0
	s_cselect_b64 s[80:81], -1, 0
	v_sub_u32_e32 v0, v0, v1
	v_lshrrev_b32_e32 v1, 28, v9
	s_lshl_b32 s40, s40, 5
	v_add_u32_e32 v1, v8, v1
	v_and_or_b32 v9, s40, 32, v72
	v_readlane_b32 s2, v254, 44
	v_lshlrev_b32_e32 v6, 4, v6
	v_lshlrev_b32_e32 v10, 4, v10
	v_ashrrev_i32_e32 v96, 4, v1
	v_and_b32_e32 v1, -16, v1
	v_lshl_add_u32 v121, v9, 2, s2
	v_mul_u32_u24_e32 v9, 0x210, v9
	s_movk_i32 s40, 0x210
	s_lshl_b32 s1, s1, 7
	v_lshl_add_u32 v13, v72, 7, s4
	v_and_b32_e32 v6, 0xf0, v6
	v_and_b32_e32 v10, 0xf0, v10
	v_lshlrev_b32_e32 v77, 4, v77
	v_lshlrev_b32_e32 v79, 4, v79
	v_lshlrev_b32_e32 v2, 4, v2
	v_lshlrev_b32_e32 v12, 4, v12
	v_sub_u32_e32 v1, v8, v1
	v_or_b32_e32 v8, s41, v72
	v_readlane_b32 s66, v253, 62
	v_add3_u32 v9, s43, v9, v75
	v_mul_lo_u32 v72, v92, s40
	v_mul_lo_u32 v75, v96, s40
	s_add_i32 s1, s2, s1
	s_lshl_b32 s0, s0, 8
	v_lshlrev_b32_e32 v3, 4, v3
	v_lshlrev_b32_e32 v4, 4, v4
	v_lshlrev_b32_e32 v5, 4, v5
	v_lshlrev_b32_e32 v7, 4, v7
	v_or_b32_e32 v15, v6, v14
	v_or_b32_e32 v76, v10, v74
	v_and_b32_e32 v77, 0x70, v77
	v_and_b32_e32 v79, 0x70, v79
	v_add_u32_e32 v14, s43, v14
	v_add_u32_e32 v74, s43, v74
	v_and_b32_e32 v2, 0xf0, v2
	v_and_b32_e32 v12, 0xf0, v12
	v_lshlrev_b32_e32 v94, 3, v0
	v_lshlrev_b32_e32 v98, 3, v1
	v_mul_u32_u24_e32 v8, 0x90, v8
	v_readlane_b32 s67, v253, 63
	v_add_u32_e32 v72, s43, v72
	v_lshlrev_b32_e32 v0, 5, v0
	v_add_u32_e32 v75, s43, v75
	v_lshlrev_b32_e32 v1, 5, v1
	s_add_i32 s1, s1, s0
	s_mov_b32 s86, 0xf800000
	v_cmp_gt_u32_e64 s[4:5], 32, v73
	v_ashrrev_i32_e32 v93, 31, v92
	v_ashrrev_i32_e32 v95, 31, v94
	v_ashrrev_i32_e32 v97, 31, v96
	v_ashrrev_i32_e32 v99, 31, v98
	v_lshl_add_u64 v[100:101], s[66:67], 0, v[160:161]
	v_lshl_add_u64 v[102:103], s[76:77], 0, v[160:161]
	v_lshl_add_u32 v122, v73, 2, s1
	s_lshl_b32 s43, s42, 7
	v_add_u32_e32 v123, 0, v15
	v_add_u32_e32 v124, 0, v76
	v_add_u32_e32 v125, v78, v77
	v_add_u32_e32 v126, v104, v79
	v_add_u32_e32 v127, v14, v6
	v_add_u32_e32 v128, v74, v10
	v_add_u32_e32 v129, v105, v2
	v_add_u32_e32 v130, v106, v12
	v_add_u32_e32 v131, v11, v8
	v_add_u32_e32 v132, v13, v3
	v_add_u32_e32 v133, v13, v4
	v_add_u32_e32 v134, v13, v5
	v_add_u32_e32 v135, v13, v7
	v_add_u32_e32 v136, s52, v9
	v_add_u32_e32 v137, v72, v0
	v_add_u32_e32 v138, v75, v1
	v_readlane_b32 s89, v253, 50
	s_mov_b32 s67, s90
	s_branch .LBB0_599

; #define REP(bit) for (int rep_ = 0; rep_ < (((DUP) & (bit)) ? 2 : 1); ++rep_)
; #define GEMM_PHASE(EPI_T, E, A_, Bt_, nM_, nN_, K_, AM) do { pg8::Gemm g{(const pg8::bf16_t*)(A_), (const pg8::bf16_t*)(Bt_), M, (nN_) * 256, (K_)}; pg8::StaticOrder S; S.init2((nM_), (nN_), (int)gridDim.x, (int)blockIdx.x); \
;         pg8::gemm_phase<EPI_T, pg8::StaticOrder, true, true, AM>(ldsl, g, S, E); } while (0)
;     int tid_ = threadIdx.x; asm volatile("" : "+v"(tid_));
;     const int tid = tid_, wid = __builtin_amdgcn_readfirstlane(tid >> 6), lane = tid & 63, wr = wid >> 2, wc = wid & 3, fr = lane & 15, fq = lane >> 4;
;     const int K = g.K, nt = K / BK;
;     unsigned voffA[2], voffB[2];
; #pragma unroll
;     for (int i = 0; i < 2; ++i) { int R, C; stage_rc(tid * 16 + i * 8192, R, C); const int Rb = Epi::PERM ? ((R & ~31) + perm32(R & 31)) : R;
;         const int Ra = AMODE ? (62 * (R >> 6) + (R & 63)) : R; voffA[i] = (unsigned)(Ra * K + C) * 2u; voffB[i] = (unsigned)(Rb * K + C) * 2u; }
;     const size_t kstep = (size_t)(BK * 2);
;     const size_t hstepB = (size_t)HALF * K * 2; const size_t hstepA = (size_t)(AMODE ? 124 : HALF) * K * 2;
;     const size_t tstepB = 2 * hstepB; const size_t tstepA = 2 * hstepA;
;     const unsigned ldsw = (unsigned)wid * 1024u;
;     const int aoff = lds_byte(wr * 64 + fr, fq * 8), boff = lds_byte(wc * 32 + fr, fq * 8);
; __global__ void __launch_bounds__(NTHR, 2) fwd_megakernel(Args args) {
;     ...
;         if constexpr (PH & 128) REP(128) { pg8::EpiRes E{even ? args.in[0] : (const float*)H, H, 1024, ((DUP) & 128) && rep_ == 0 ? zopq : 1.f}; GEMM_PHASE(pg8::EpiRes, E, OUTB, ws + (even ? WS_WOUTE : WS_WOUTO), 128, 4, 1024, 0); }
.Lnb_done_7:
.LBB0_659:
	s_or_b64 exec, exec, s[0:1]
	v_readlane_b32 s8, v253, 4
	v_readlane_b32 s9, v253, 5
	s_waitcnt lgkmcnt(0)
	s_barrier
	s_mov_b64 s[4:5], 0x900000
	v_readlane_b32 s10, v253, 6
	v_readlane_b32 s11, v253, 7
	v_readlane_b32 s12, v253, 8
	v_readlane_b32 s13, v253, 9
	v_readlane_b32 s14, v253, 10
	v_readlane_b32 s15, v253, 11
	v_readlane_b32 s16, v253, 12
	v_readlane_b32 s17, v253, 13
	v_readlane_b32 s18, v253, 14
	v_readlane_b32 s19, v253, 15
	v_readlane_b32 s20, v253, 16
	v_readlane_b32 s21, v253, 17
	v_readlane_b32 s22, v253, 18
	v_readlane_b32 s23, v253, 19
	s_mov_b64 s[0:1], s[8:9]
	s_mov_b64 s[42:43], 0x3400

; DI void norm_phase(const Ctx& c, const float* __restrict__ h, const float* __restrict__ g, bf16* __restrict__ xn) {
;     const f32x4* gr = (const f32x4*)g + c.lane;
;     f32x4 gg[4];
; #pragma unroll
;     for (int j = 0; j < 4; ++j) gg[j] = gr[64 * j];
;     for (int m0 = c.gw * 4; m0 < M; m0 += c.NGW * 4) {
;         f32x4 v[4][4];
; #pragma unroll
;         for (int r = 0; r < 4; ++r) { const f32x4* xr = (const f32x4*)(h + (size_t)(m0 + r) * D) + c.lane;
; #pragma unroll
;             for (int j = 0; j < 4; ++j) v[r][j] = __builtin_nontemporal_load(xr + 64 * j); }
; #pragma unroll
;         for (int r = 0; r < 4; ++r) {
;             float s = 0.f;
; #pragma unroll
;             for (int j = 0; j < 4; ++j) s += (v[r][j].x * v[r][j].x + v[r][j].y * v[r][j].y) + (v[r][j].z * v[r][j].z + v[r][j].w * v[r][j].w);
;             const float rstd = 1.f / sqrtf(wave_sum(s) * (1.f / 1024.f) + 1e-6f);
.Lnb_done_8:
.LBB0_733:
	s_or_b64 exec, exec, s[0:1]
	s_waitcnt lgkmcnt(0)
	v_mov_b32_e32 v0, v186
	s_barrier
	s_nop 0
	v_readfirstlane_b32 s0, v0
	s_ashr_i32 s0, s0, 6
	s_add_i32 s0, s0, s72
	s_cmpk_lt_i32 s0, 0x2000
	s_cbranch_scc0 .LBB0_736
	s_lshl_b32 s2, s64, 10
	v_readlane_b32 s8, v253, 20
	s_lshl_b64 s[4:5], s[2:3], 2
	v_readlane_b32 s16, v253, 28
	v_readlane_b32 s17, v253, 29
	s_add_u32 s4, s16, s4
	v_and_b32_e32 v16, 63, v0
	s_addc_u32 s5, s17, s5
	v_lshlrev_b32_e32 v160, 4, v16
	global_load_dwordx4 v[0:3], v160, s[4:5] offset:3072
	global_load_dwordx4 v[4:7], v160, s[4:5] offset:2048
	global_load_dwordx4 v[8:11], v160, s[4:5] offset:1024
	global_load_dwordx4 v[12:15], v160, s[4:5]
	v_and_b32_e32 v17, 64, v193
	v_add_u32_e32 v17, 64, v17
	v_xor_b32_e32 v18, 1, v193
	v_cmp_lt_i32_e32 vcc, v18, v17
	s_load_dword s1, s[70:71], 0x0
	s_lshl_b32 s6, s0, 2
	v_cndmask_b32_e32 v18, v193, v18, vcc
	s_waitcnt vmcnt(15)
	v_lshlrev_b32_e32 v81, 2, v18
	v_xor_b32_e32 v18, 2, v193
	v_cmp_lt_i32_e32 vcc, v18, v17
	s_ashr_i32 s7, s6, 31
	s_waitcnt lgkmcnt(0)
	s_lshl_b32 s4, s1, 5
	v_cndmask_b32_e32 v18, v193, v18, vcc
	s_waitcnt vmcnt(14)
	v_lshlrev_b32_e32 v84, 2, v18
	v_xor_b32_e32 v18, 4, v193
	v_cmp_lt_i32_e32 vcc, v18, v17
	s_lshl_b64 s[0:1], s[6:7], 11
	v_readlane_b32 s2, v254, 38
	v_cndmask_b32_e32 v18, v193, v18, vcc
	v_lshlrev_b32_e32 v85, 2, v18
	v_xor_b32_e32 v18, 8, v193
	v_cmp_lt_i32_e32 vcc, v18, v17
	s_add_u32 s0, s2, s0
	v_readlane_b32 s2, v254, 39
	v_cndmask_b32_e32 v18, v193, v18, vcc
	v_lshlrev_b32_e32 v86, 2, v18
	v_xor_b32_e32 v18, 16, v193
	v_cmp_lt_i32_e32 vcc, v18, v17
	v_readlane_b32 s9, v253, 21
	v_lshlrev_b32_e32 v16, 3, v16
	v_cndmask_b32_e32 v18, v193, v18, vcc
	v_lshlrev_b32_e32 v87, 2, v18
	v_xor_b32_e32 v18, 32, v193
	v_cmp_lt_i32_e32 vcc, v18, v17
	s_addc_u32 s1, s2, s1
	s_ashr_i32 s5, s4, 31
	v_cndmask_b32_e32 v17, v193, v18, vcc
	s_waitcnt vmcnt(13)
	v_lshlrev_b32_e32 v88, 2, v17
	v_mov_b32_e32 v17, v161
	v_lshl_add_u64 v[76:77], s[0:1], 0, v[16:17]
	s_lshl_b64 s[8:9], s[4:5], 11
	s_lshl_b64 s[0:1], s[6:7], 12
	v_readlane_b32 s2, v254, 40
	s_add_u32 s0, s2, s0
	v_readlane_b32 s2, v254, 41
	v_readlane_b32 s10, v253, 22
	v_readlane_b32 s11, v253, 23
	s_addc_u32 s1, s2, s1
	v_lshl_add_u64 v[78:79], s[0:1], 0, v[160:161]
	s_lshl_b64 s[10:11], s[4:5], 12
	s_movk_i32 s2, 0xf000
	v_readlane_b32 s12, v253, 24
	v_readlane_b32 s13, v253, 25
	v_readlane_b32 s14, v253, 26
	v_readlane_b32 s15, v253, 27
	v_readlane_b32 s18, v253, 30
	v_readlane_b32 s19, v253, 31
	v_readlane_b32 s20, v253, 32
	v_readlane_b32 s21, v253, 33
	v_readlane_b32 s22, v253, 34
	v_readlane_b32 s23, v253, 35

; #define REP(bit) for (int rep_ = 0; rep_ < (((DUP) & (bit)) ? 2 : 1); ++rep_)
; #define GEMM_PHASE(EPI_T, E, A_, Bt_, nM_, nN_, K_, AM) do { pg8::Gemm g{(const pg8::bf16_t*)(A_), (const pg8::bf16_t*)(Bt_), M, (nN_) * 256, (K_)}; pg8::StaticOrder S; S.init2((nM_), (nN_), (int)gridDim.x, (int)blockIdx.x); \
;         pg8::gemm_phase<EPI_T, pg8::StaticOrder, true, true, AM>(ldsl, g, S, E); } while (0)
; __global__ void __launch_bounds__(NTHR, 2) fwd_megakernel(Args args) {
;     ...
;         if constexpr (PH & 1024) REP(1024) { pg8::EpiConvGate E{(pg8::bf16_t*)ACT, args.in[14] + (size_t)layer * 3 * DFF, args.in[15] + (size_t)layer * DFF, M};
;           GEMM_PHASE(pg8::EpiConvGate, E, XN - 2 * 1024, ws + (even ? WS_WUP0 : WS_WUP1), 133, 22, 1024, 1); }
.Lnb_done_9:
.LBB0_789:
	s_or_b64 exec, exec, s[0:1]
	s_waitcnt lgkmcnt(0)
	s_barrier
	s_load_dword s34, s[70:71], 0x0
	v_readlane_b32 s4, v254, 12
	v_mov_b32_e32 v14, v186
	v_readlane_b32 s5, v254, 13
	s_and_b64 vcc, exec, s[4:5]
	v_readfirstlane_b32 s0, v14
	s_cbranch_vccz .LBB0_791
	v_readlane_b32 s1, v254, 36
	s_mov_b32 s26, s1
	v_readlane_b32 s80, v254, 32

; #define PG8_STAGE(bufoff, gbase, voff) do { _Pragma("unroll") for (int _i = 0; _i < 2; ++_i) \
;         __builtin_amdgcn_global_load_lds((const unsigned*)((const char*)(gbase) + (voff)[_i]), (PG8_LAS unsigned*)(lds + (bufoff) + ldsw + _i * 8192), 16, 0, 0); } while (0)
; #define PG8_WAIT_V(n) asm volatile("s_waitcnt vmcnt(" #n ")" ::: "memory")
; #define PG8_BAR __builtin_amdgcn_s_barrier()
;     ...
;     for (int i = 0; i < 2; ++i) { int R, C; stage_rc(tid * 16 + i * 8192, R, C); const int Rb = Epi::PERM ? ((R & ~31) + perm32(R & 31)) : R;
;         const int Ra = AMODE ? (62 * (R >> 6) + (R & 63)) : R; voffA[i] = (unsigned)(Ra * K + C) * 2u; voffB[i] = (unsigned)(Rb * K + C) * 2u; }
;     const size_t kstep = (size_t)(BK * 2);
;     const size_t hstepB = (size_t)HALF * K * 2; const size_t hstepA = (size_t)(AMODE ? 124 : HALF) * K * 2;
;     const size_t tstepB = 2 * hstepB; const size_t tstepA = 2 * hstepA;
;     const unsigned ldsw = (unsigned)wid * 1024u;
;     const int aoff = lds_byte(wr * 64 + fr, fq * 8), boff = lds_byte(wc * 32 + fr, fq * 8);
;     ...
;     Unit cur, nxt; int ui = 0;
;     if (!S.next(0, cur)) return;
;     f32x4 acc[2][2][4][2];
; #pragma unroll
;     for (int a = 0; a < 2; ++a)
; #pragma unroll
;         for (int b = 0; b < 2; ++b)
; #pragma unroll
;             for (int m = 0; m < 4; ++m)
; #pragma unroll
;                 for (int n = 0; n < 2; ++n) acc[a][b][m][n] = (f32x4){0.f, 0.f, 0.f, 0.f};
;     bf16x8 At[4][2], B0[2][2], B1[2][2];
;     const char* cA = (const char*)g.A + (size_t)cur.pm * tstepA; const char* cB = (const char*)g.Bt + (size_t)cur.pn * tstepB;
;     S.a_ready(cur);
;     if constexpr (SP2) {
;         PG8_STAGE(PG8_SB(0, 0), cB, voffB); PG8_STAGE(PG8_SB(0, 1), cB + hstepB, voffB); PG8_STAGE(PG8_SA(0, 0), cA, voffA); PG8_STAGE(PG8_SA(0, 1), cA + hstepA, voffA);
;         if (wr == 1) PG8_BAR;
;         PG8_WAIT_V(2); PG8_BAR;
;         PG8_STAGE(PG8_SB(1, 0), cB + kstep, voffB); PG8_STAGE(PG8_SA(1, 0), cA + kstep, voffA); PG8_STAGE(PG8_SB(1, 1), cB + hstepB + kstep, voffB);
.Lnb_done_10:
.LBB0_882:
	s_or_b64 exec, exec, s[0:1]
	v_readlane_b32 s4, v253, 42
	v_mov_b32_e32 v12, v186
	v_readlane_b32 s5, v253, 43
	s_waitcnt lgkmcnt(0)
	s_barrier
	s_and_b64 vcc, exec, s[4:5]
	v_readfirstlane_b32 s0, v12
	s_cbranch_vccz .LBB0_906
	v_lshlrev_b32_e32 v0, 4, v12
	v_add_u32_e32 v1, 0x2000, v0
	v_ashrrev_i32_e32 v2, 31, v1
	v_lshrrev_b32_e32 v2, 22, v2
	v_add_u32_e32 v2, v1, v2
	v_ashrrev_i32_e32 v4, 10, v2
	v_mul_i32_i24_e32 v2, 0x400, v4
	v_sub_u32_e32 v1, v1, v2
	v_lshrrev_b32_e32 v2, 4, v1
	v_bitop3_b32 v1, v2, v1, 32 bitop3:0x6c
	v_ashrrev_i32_e32 v2, 31, v1
	v_lshrrev_b32_e32 v2, 26, v2
	v_add_u32_e32 v2, v1, v2
	v_ashrrev_i32_e32 v5, 6, v2
	v_and_b32_e32 v2, 0xc0, v2
	v_sub_u32_e32 v1, v1, v2
	v_ashrrev_i16_sdwa v1, v191, sext(v1) dst_sel:DWORD dst_unused:UNUSED_PAD src0_sel:DWORD src1_sel:BYTE_0
	v_bfe_i32 v7, v1, 0, 16
	v_bfe_i32 v1, v12, 27, 1
	v_lshrrev_b32_e32 v1, 22, v1
	v_add_u32_e32 v1, v0, v1
	v_and_b32_e32 v1, 0xfffffc00, v1
	v_sub_u32_e32 v0, v0, v1
	v_lshrrev_b32_e32 v1, 4, v0
	v_ashrrev_i32_e32 v2, 31, v12
	v_bitop3_b32 v0, v1, v0, 32 bitop3:0x6c
	v_lshrrev_b32_e32 v2, 26, v2
	v_readlane_b32 s4, v254, 61
	v_ashrrev_i32_e32 v1, 31, v0
	v_add_u32_e32 v2, v12, v2
	v_readlane_b32 s5, v254, 62
	v_lshlrev_b32_e32 v3, 3, v4
	v_lshrrev_b32_e32 v1, 26, v1
	v_ashrrev_i32_e32 v9, 6, v2
	s_and_b64 s[4:5], s[4:5], exec
	s_mov_b32 s1, 0x2a00000
	v_and_b32_e32 v3, 0xfffff0, v3
	v_add_u32_e32 v1, v0, v1
	v_lshlrev_b32_e32 v2, 3, v9
	s_cselect_b32 s1, s1, 0x3000000
	v_add_u32_e32 v3, v5, v3
	s_movk_i32 s2, 0xb00
	v_lshlrev_b32_e32 v6, 5, v4
	v_ashrrev_i32_e32 v8, 6, v1
	v_and_b32_e32 v2, 0xfffff0, v2
	s_add_u32 s20, s46, s1
	v_mul_lo_u32 v3, v3, s2
	v_and_b32_e32 v6, 32, v6
	v_add_u32_e32 v2, v8, v2
	s_addc_u32 s21, s47, 0
	s_ashr_i32 s1, s0, 6
	v_or_b32_e32 v3, v3, v6
	v_mul_lo_u32 v2, v2, s2
	v_and_b32_e32 v1, 0xc0, v1
	v_readlane_b32 s2, v254, 17
	s_ashr_i32 s4, s0, 8
	s_lshl_b32 s22, s1, 10
	v_add_lshl_u32 v128, v3, v7, 1
	v_lshlrev_b32_e32 v3, 5, v9
	v_sub_u32_e32 v0, v0, v1
	s_mul_i32 s5, s2, 0x160000
	v_and_b32_e32 v10, 32, v3
	v_ashrrev_i16_sdwa v0, v191, sext(v0) dst_sel:DWORD dst_unused:UNUSED_PAD src0_sel:DWORD src1_sel:BYTE_0
	s_add_u32 s14, s20, s5
	s_mul_hi_i32 s5, s2, 0x160000
	v_or_b32_e32 v2, v2, v10
	v_bfe_i32 v11, v0, 0, 16
	s_addc_u32 s15, s21, s5
	s_add_i32 s23, s22, 0
	v_add_lshl_u32 v160, v2, v11, 1
	s_add_i32 m0, s23, 0x10000
	s_load_dword s27, s[70:71], 0x0
	global_load_lds_dwordx4 v160, s[14:15]
	s_add_i32 m0, s23, 0x12000
	s_add_u32 s6, s14, 0xb0000
	global_load_lds_dwordx4 v128, s[14:15]
	s_addc_u32 s7, s15, 0
	s_add_i32 m0, s23, 0x14000
	s_add_i32 s24, s23, 0x2000
	global_load_lds_dwordx4 v160, s[6:7]
	s_add_i32 m0, s23, 0x16000
	s_add_i32 s25, s23, 0x4000
	global_load_lds_dwordx4 v128, s[6:7]
	v_readlane_b32 s6, v254, 28
	s_mov_b32 m0, s23
	v_readlane_b32 s7, v254, 29
	s_add_i32 s26, s23, 0x6000
	v_mov_b32_e32 v129, v161
	s_cmp_eq_u32 s4, 1
	v_lshl_add_u64 v[0:1], s[14:15], 0, v[160:161]
	v_lshl_add_u64 v[2:3], s[14:15], 0, v[128:129]
	global_load_lds_dwordx4 v160, s[6:7]
	s_mov_b32 m0, s24
	s_nop 0
	global_load_lds_dwordx4 v128, s[6:7]
	v_readlane_b32 s6, v254, 30
	s_mov_b32 m0, s25
	v_readlane_b32 s7, v254, 31
	s_nop 4
	global_load_lds_dwordx4 v160, s[6:7]
	s_mov_b32 m0, s26
	s_nop 0
	global_load_lds_dwordx4 v128, s[6:7]
	s_cselect_b64 s[6:7], -1, 0
	s_cmp_lg_u32 s4, 1
	s_cbranch_scc1 .LBB0_885
	s_barrier

; DI void norm_phase(const Ctx& c, const float* __restrict__ h, const float* __restrict__ g, bf16* __restrict__ xn) {
;     const f32x4* gr = (const f32x4*)g + c.lane;
;     f32x4 gg[4];
; #pragma unroll
;     for (int j = 0; j < 4; ++j) gg[j] = gr[64 * j];
;     for (int m0 = c.gw * 4; m0 < M; m0 += c.NGW * 4) {
;         f32x4 v[4][4];
; #pragma unroll
;         for (int r = 0; r < 4; ++r) { const f32x4* xr = (const f32x4*)(h + (size_t)(m0 + r) * D) + c.lane;
; #pragma unroll
;             for (int j = 0; j < 4; ++j) v[r][j] = __builtin_nontemporal_load(xr + 64 * j); }
; #pragma unroll
;         for (int r = 0; r < 4; ++r) {
;             float s = 0.f;
; #pragma unroll
;             for (int j = 0; j < 4; ++j) s += (v[r][j].x * v[r][j].x + v[r][j].y * v[r][j].y) + (v[r][j].z * v[r][j].z + v[r][j].w * v[r][j].w);
;             const float rstd = 1.f / sqrtf(wave_sum(s) * (1.f / 1024.f) + 1e-6f);
; __global__ void __launch_bounds__(NTHR, 2) fwd_megakernel(Args args) {
;     ...
;             norm_phase(mkctx(lds), H, args.in[1] + 1024, XN);
.Lnb_done_11:
.LBB0_959:
	s_or_b64 exec, exec, s[0:1]
	s_waitcnt lgkmcnt(0)
	v_mov_b32_e32 v0, v186
	s_barrier
	s_load_dword s14, s[70:71], 0x0
	v_readfirstlane_b32 s0, v0
	s_ashr_i32 s0, s0, 6
	s_add_i32 s0, s0, s72
	s_cmpk_gt_i32 s0, 0x1fff
	s_cbranch_scc1 .LBB0_962
	v_and_b32_e32 v16, 63, v0
	v_readlane_b32 s4, v254, 14
	v_lshlrev_b32_e32 v160, 4, v16
	v_readlane_b32 s5, v254, 15
	s_nop 4
	global_load_dwordx4 v[0:3], v160, s[4:5] offset:3072
	global_load_dwordx4 v[4:7], v160, s[4:5] offset:2048
	global_load_dwordx4 v[8:11], v160, s[4:5] offset:1024
	global_load_dwordx4 v[12:15], v160, s[4:5]
	v_and_b32_e32 v17, 64, v193
	v_add_u32_e32 v17, 64, v17
	v_xor_b32_e32 v18, 1, v193
	v_cmp_lt_i32_e32 vcc, v18, v17
	s_lshl_b32 s8, s0, 2
	s_ashr_i32 s9, s8, 31
	v_cndmask_b32_e32 v18, v193, v18, vcc
	v_lshlrev_b32_e32 v81, 2, v18
	v_xor_b32_e32 v18, 2, v193
	v_cmp_lt_i32_e32 vcc, v18, v17
	s_waitcnt lgkmcnt(0)
	s_lshl_b32 s4, s14, 5
	s_lshl_b64 s[0:1], s[8:9], 11
	v_cndmask_b32_e32 v18, v193, v18, vcc
	v_lshlrev_b32_e32 v84, 2, v18
	v_xor_b32_e32 v18, 4, v193
	v_cmp_lt_i32_e32 vcc, v18, v17
	v_readlane_b32 s2, v254, 38
	s_add_u32 s0, s2, s0
	v_cndmask_b32_e32 v18, v193, v18, vcc
	v_lshlrev_b32_e32 v85, 2, v18
	v_xor_b32_e32 v18, 8, v193
	v_cmp_lt_i32_e32 vcc, v18, v17
	v_readlane_b32 s2, v254, 39
	v_lshlrev_b32_e32 v16, 3, v16
	v_cndmask_b32_e32 v18, v193, v18, vcc
	v_lshlrev_b32_e32 v86, 2, v18
	v_xor_b32_e32 v18, 16, v193
	v_cmp_lt_i32_e32 vcc, v18, v17
	s_addc_u32 s1, s2, s1
	s_ashr_i32 s5, s4, 31
	v_cndmask_b32_e32 v18, v193, v18, vcc
	v_lshlrev_b32_e32 v87, 2, v18
	v_xor_b32_e32 v18, 32, v193
	v_cmp_lt_i32_e32 vcc, v18, v17
	s_lshl_b64 s[10:11], s[4:5], 11
	v_readlane_b32 s2, v254, 40
	v_cndmask_b32_e32 v17, v193, v18, vcc
	v_lshlrev_b32_e32 v88, 2, v17
	v_mov_b32_e32 v17, v161
	v_lshl_add_u64 v[76:77], s[0:1], 0, v[16:17]
	s_lshl_b64 s[0:1], s[8:9], 12
	s_add_u32 s0, s2, s0
	v_readlane_b32 s2, v254, 41
	s_addc_u32 s1, s2, s1
	v_lshl_add_u64 v[78:79], s[0:1], 0, v[160:161]
	s_lshl_b64 s[12:13], s[4:5], 12
	s_movk_i32 s2, 0xf000

; #define GSYNC() do { XcdBarrier b_; b_.bar = (unsigned*)args.ws; b_.x = xb_xcc_id(); b_.st = (volatile LAS unsigned*)((LAS unsigned char*)lds + LDS_BYTES - 64) + 8; xcd_barrier(b_); if constexpr ((DUP) & 0x10000) xcd_barrier(b_); } while (0)
; __global__ void __launch_bounds__(NTHR, 2) fwd_megakernel(Args args) {
;     ...
;             GSYNC();
;         }
;     }
.Lnb_done_12:
	s_branch .LBB0_117
